# adds DPP/readlane sum-of-squares all-reduce in phase 1, WgT gate-column loads before the adaLN sums, passA next-chunk requests before the LDS drain barrier; K-loop byte phases kept at the baseline's
# speedup vs baseline: 1.0046x; 1.0040x over previous
; #define LAS __attribute__((address_space(3)))
; __device__ __forceinline__ int opaque_tid() { int t = (int)threadIdx.x; asm volatile("" : "+v"(t)); return t; }
; __device__ void phase1(const Params& p, LAS unsigned char* lds) {
;     const int tid = opaque_tid(), wid = tid >> 6, lane = tid & 63;
;     LAS float* gs = (LAS float*)lds; LAS float* sh = gs + 1024; LAS float* gsc = sh + 1024; LAS float* shc = gsc + 1024; LAS float* WgT = shc + 1024;
;     const float* modp = (const float*)(p.ws + OFF_MODP);
;     bf16_t* AB = (bf16_t*)(p.ws + OFF_AB);
.LBB0_87:
	s_or_b64 exec, exec, s[4:5]
	s_load_dwordx16 s[4:19], s[0:1], 0x40
	s_andn2_b64 vcc, exec, s[24:25]
	v_mbcnt_lo_u32_b32 v158, -1, 0
	s_waitcnt lgkmcnt(0)
	s_barrier
	v_writelane_b32 v254, s4, 6
	s_nop 1
	v_writelane_b32 v254, s5, 7
	v_writelane_b32 v254, s6, 8
	v_writelane_b32 v254, s7, 9
	v_writelane_b32 v254, s8, 10
	v_writelane_b32 v254, s9, 11
	v_writelane_b32 v254, s10, 12
	v_writelane_b32 v254, s11, 13
	v_writelane_b32 v254, s12, 14
	v_writelane_b32 v254, s13, 15
	v_writelane_b32 v254, s14, 16
	v_writelane_b32 v254, s15, 17
	v_writelane_b32 v254, s16, 18
	v_writelane_b32 v254, s17, 19
	v_writelane_b32 v254, s18, 20
	v_writelane_b32 v254, s19, 21
	v_writelane_b32 v254, s20, 22
	s_nop 1
	v_writelane_b32 v254, s21, 23
	s_cbranch_vccnz .LBB0_113
	s_waitcnt vmcnt(1)
; #define LAS __attribute__((address_space(3)))
; __device__ __forceinline__ int opaque_tid() { int t = (int)threadIdx.x; asm volatile("" : "+v"(t)); return t; }
; __device__ void phase1(const Params& p, LAS unsigned char* lds) {
;     const int tid = opaque_tid(), wid = tid >> 6, lane = tid & 63;
;     LAS float* gs = (LAS float*)lds; LAS float* sh = gs + 1024; LAS float* gsc = sh + 1024; LAS float* shc = gsc + 1024; LAS float* WgT = shc + 1024;
;     const float* modp = (const float*)(p.ws + OFF_MODP);
;     bf16_t* AB = (bf16_t*)(p.ws + OFF_AB);
;     if (tid < 64) {
;         unsigned spins = 0;
;         while ((unsigned)__builtin_amdgcn_readfirstlane(__hip_atomic_load((unsigned*)(p.ws + OFF_ACNT), __ATOMIC_RELAXED, __HIP_MEMORY_SCOPE_AGENT)) < gridDim.x) { __builtin_amdgcn_s_sleep(2); if (++spins > (1u << 22)) break; }
;         __builtin_amdgcn_fence(__ATOMIC_ACQUIRE, "agent"); asm volatile("s_waitcnt vmcnt(0)" ::: "memory"); }
;     __syncthreads();
;     for (int job = blockIdx.x; job < 256; job += gridDim.x) {
;         const int b = job >> 5;
;         for (int i = tid; i < 1024; i += 512) {
;             float s0 = p.ada_b[i], s1 = p.ada_b[1024 + i], s2 = p.ada_b[2048 + i], c0 = s0, c1 = s1;
; #pragma unroll
;             for (int ks = 0; ks < 8; ++ks) { const float* mp = modp + (size_t)(ks * 9 + b) * 3072; s0 += mp[i]; s1 += mp[1024 + i]; s2 += mp[2048 + i];
;                 const float* mc = modp + (size_t)(ks * 9 + 8) * 3072; c0 += mc[i]; c1 += mc[1024 + i]; }
;             const float nw = p.norm_w[i];
;             gs[i] = nw * (1.0f + s1); sh[i] = s0; gsc[i] = nw * (1.0f + c1); shc[i] = c0;
;             if ((job & 31) == 0) ((float*)(p.ws + OFF_GATEV))[b * 1024 + i] = s2;
;         }
;         for (int i = tid; i < 16384; i += 512) { const int j = i & 15, k = i >> 4; WgT[j * 1024 + k] = p.in_w[(size_t)k * 8208 + 5120 + j]; }
	v_mbcnt_hi_u32_b32 v4, -1, v158
	v_and_b32_e32 v7, 64, v4
	v_xor_b32_e32 v5, 32, v4
	v_add_u32_e32 v7, 64, v7
	v_cmp_lt_i32_e32 vcc, v5, v7
	v_and_b32_e32 v6, 63, v32
	v_mov_b32_e32 v35, 0
	v_cndmask_b32_e32 v5, v4, v5, vcc
	v_lshlrev_b32_e32 v53, 2, v5
	v_xor_b32_e32 v5, 16, v4
	v_cmp_lt_i32_e32 vcc, v5, v7
	v_lshlrev_b32_e32 v34, 13, v6
	v_lshlrev_b32_e32 v0, 10, v6
	v_cndmask_b32_e32 v5, v4, v5, vcc
	v_lshlrev_b32_e32 v94, 2, v5
	v_xor_b32_e32 v5, 8, v4
	v_cmp_lt_i32_e32 vcc, v5, v7
	v_mov_b32_e32 v1, v35
	s_mov_b64 s[18:19], 0xfc00000
	v_cndmask_b32_e32 v5, v4, v5, vcc
	v_lshlrev_b32_e32 v95, 2, v5
	v_xor_b32_e32 v5, 4, v4
	v_cmp_lt_i32_e32 vcc, v5, v7
	v_lshl_add_u64 v[0:1], s[70:71], 0, v[0:1]
	v_readlane_b32 s52, v254, 6
	v_cndmask_b32_e32 v5, v4, v5, vcc
	v_lshlrev_b32_e32 v96, 2, v5
	v_xor_b32_e32 v5, 2, v4
	v_cmp_lt_i32_e32 vcc, v5, v7
	s_movk_i32 s3, 0x4000
	v_lshlrev_b32_e32 v2, 2, v6
	v_cndmask_b32_e32 v5, v4, v5, vcc
	v_lshlrev_b32_e32 v97, 2, v5
	v_xor_b32_e32 v5, 1, v4
	v_cmp_lt_i32_e32 vcc, v5, v7
	v_mov_b32_e32 v3, v35
	v_readlane_b32 s53, v254, 7
	v_cndmask_b32_e32 v4, v4, v5, vcc
	v_lshlrev_b32_e32 v98, 2, v4
	v_lshlrev_b32_e32 v4, 3, v6
	v_mov_b32_e32 v5, v35
	v_lshl_add_u64 v[36:37], s[70:71], 0, v[4:5]
	v_and_b32_e32 v4, 8, v32
	v_cmp_eq_u32_e64 s[6:7], 0, v4
	v_and_b32_e32 v4, 4, v32
	v_cmp_eq_u32_e64 s[8:9], 0, v4
	v_cmp_ne_u32_e64 s[10:11], 0, v4
	v_and_b32_e32 v4, 2, v32
	v_cmp_eq_u32_e64 s[12:13], 0, v4
	v_and_b32_e32 v4, 1, v32
	v_cmp_eq_u32_e64 s[14:15], 0, v4
	v_lshl_add_u64 v[4:5], s[70:71], 0, v[34:35]
	v_lshl_add_u64 v[40:41], v[4:5], 0, s[18:19]
	s_mov_b64 s[18:19], 0xfd00000
	v_lshl_add_u64 v[42:43], v[0:1], 0, s[18:19]
	v_max_i32_e32 v0, 0x3e00, v32
	v_sub_u32_e32 v0, v0, v32
	v_add_u32_e32 v0, 0x1ff, v0
	v_lshrrev_b32_e32 v1, 9, v0
	v_cmp_gt_i32_e64 s[4:5], s3, v32
	v_lshl_add_u64 v[44:45], s[52:53], 0, v[2:3]
	s_movk_i32 s3, 0x1ff
	v_add_u32_e32 v3, 1, v1
	v_add_u32_e32 v1, -1, v1
	v_ashrrev_i32_e32 v39, 6, v32
	v_lshrrev_b32_e32 v4, 1, v1
	v_cmp_lt_u32_e64 s[18:19], s3, v0
	v_and_b32_e32 v0, 0xfffffe, v3
	v_cmp_lt_u32_e64 s[20:21], 1, v1
	v_and_b32_e32 v1, 2, v1
	s_movk_i32 s0, 0x400
	v_lshlrev_b32_e32 v51, 3, v39
	v_lshl_add_u32 v99, v6, 4, 0
	v_and_b32_e32 v38, 15, v32
	s_add_u32 s42, s70, 0xfef9000
	v_add_u32_e32 v4, 1, v4
	v_lshl_add_u32 v102, v0, 9, v32
	v_cmp_eq_u32_e64 s[22:23], 0, v1
	v_cmp_ne_u32_e64 s[24:25], v3, v0
	v_ashrrev_i32_e32 v1, 31, v32
	v_mov_b32_e32 v0, v32
	v_cmp_gt_i32_e64 s[0:1], s0, v32
	v_add_u32_e32 v100, 0x4000, v99
	v_cmp_gt_u32_e64 s[16:17], 16, v6
	v_lshl_add_u32 v101, v38, 12, 0
	s_addc_u32 s43, s71, 0
	v_add_u32_e32 v33, 0x200, v32
	v_and_b32_e32 v103, -2, v4
	v_lshl_add_u32 v104, v32, 2, 0
	v_lshlrev_b64 v[46:47], 2, v[0:1]
	s_and_b32 s93, s2, 7
	s_lshl_b32 s93, s93, 5
	s_lshr_b32 s94, s2, 3
	s_add_u32 s93, s93, s94
	v_lshl_add_u32 v105, s93, 6, v51
	s_lshl_b32 s26, s72, 6
	s_mov_b32 s27, 0x8040
	s_movk_i32 s33, 0x5000
	v_lshlrev_b32_e32 v48, 2, v2
	s_mov_b32 s46, 0x3a800000
	s_mov_b32 s34, 0x800000
	s_mov_b32 s35, 0xbfb8aa3b
	s_mov_b32 s47, 0xb2a5705f
	s_mov_b32 s53, 0x42ce8ed0
	s_mov_b32 s75, 0xc2b17218
	s_mov_b32 s77, 0x7f800000
	s_mov_b32 s79, 0x3f2aaaab
	s_mov_b32 s52, 0x3e9b6dac
	s_mov_b32 s74, 0x3f2aaada
	s_mov_b32 s76, 0x3f317218
	s_mov_b32 s78, 0xb102e308
	s_mov_b32 s92, 0x33800000
	v_mov_b32_e32 v106, 2
	v_mov_b32_e32 v50, 0x358637bd
	v_mov_b32_e32 v107, 0x7f800000
	v_mov_b32_e32 v52, 0x3ecc95a3
	v_readlane_b32 s54, v254, 8
	v_readlane_b32 s55, v254, 9
	v_readlane_b32 s56, v254, 10
	v_readlane_b32 s57, v254, 11
	v_readlane_b32 s58, v254, 12
	v_readlane_b32 s59, v254, 13
	v_readlane_b32 s60, v254, 14
	v_readlane_b32 s61, v254, 15
	v_readlane_b32 s62, v254, 16
	v_readlane_b32 s63, v254, 17
	v_readlane_b32 s64, v254, 18
	v_readlane_b32 s65, v254, 19
	v_readlane_b32 s66, v254, 20
	v_readlane_b32 s67, v254, 21
	v_lshrrev_b32_e32 v110, 4, v32
	v_mul_u32_u24_e32 v111, 0x8040, v110
	v_lshl_add_u32 v111, v38, 2, v111
	v_add_u32_e32 v111, 0x5000, v111
	v_lshl_add_u32 v110, v110, 2, v101
	s_mov_b64 s[38:39], s[50:51]
	global_load_dword v112, v111, s[38:39]
	s_add_u32 s38, s38, 0x100800
	s_addc_u32 s39, s39, 0
	global_load_dword v113, v111, s[38:39]
	s_add_u32 s38, s38, 0x100800
	s_addc_u32 s39, s39, 0
	global_load_dword v114, v111, s[38:39]
	s_add_u32 s38, s38, 0x100800
	s_addc_u32 s39, s39, 0
	global_load_dword v115, v111, s[38:39]
	s_add_u32 s38, s38, 0x100800
	s_addc_u32 s39, s39, 0
	global_load_dword v116, v111, s[38:39]
	s_add_u32 s38, s38, 0x100800
	s_addc_u32 s39, s39, 0
	global_load_dword v117, v111, s[38:39]
	s_add_u32 s38, s38, 0x100800
	s_addc_u32 s39, s39, 0
	global_load_dword v118, v111, s[38:39]
	s_add_u32 s38, s38, 0x100800
	s_addc_u32 s39, s39, 0
	global_load_dword v119, v111, s[38:39]
	s_add_u32 s38, s38, 0x100800
	s_addc_u32 s39, s39, 0
	global_load_dword v120, v111, s[38:39]
	s_add_u32 s38, s38, 0x100800
	s_addc_u32 s39, s39, 0
	global_load_dword v121, v111, s[38:39]
	s_add_u32 s38, s38, 0x100800
	s_addc_u32 s39, s39, 0
	global_load_dword v122, v111, s[38:39]
	s_add_u32 s38, s38, 0x100800
	s_addc_u32 s39, s39, 0
	global_load_dword v123, v111, s[38:39]
	s_add_u32 s38, s38, 0x100800
	s_addc_u32 s39, s39, 0
	global_load_dword v124, v111, s[38:39]
	s_add_u32 s38, s38, 0x100800
	s_addc_u32 s39, s39, 0
	global_load_dword v125, v111, s[38:39]
	s_add_u32 s38, s38, 0x100800
	s_addc_u32 s39, s39, 0
	global_load_dword v126, v111, s[38:39]
	s_add_u32 s38, s38, 0x100800
	s_addc_u32 s39, s39, 0
	global_load_dword v127, v111, s[38:39]
	s_add_u32 s38, s38, 0x100800
	s_addc_u32 s39, s39, 0
	global_load_dword v128, v111, s[38:39]
	s_add_u32 s38, s38, 0x100800
	s_addc_u32 s39, s39, 0
	global_load_dword v129, v111, s[38:39]
	s_add_u32 s38, s38, 0x100800
	s_addc_u32 s39, s39, 0
	global_load_dword v130, v111, s[38:39]
	s_add_u32 s38, s38, 0x100800
	s_addc_u32 s39, s39, 0
	global_load_dword v131, v111, s[38:39]
	s_add_u32 s38, s38, 0x100800
	s_addc_u32 s39, s39, 0
	global_load_dword v132, v111, s[38:39]
	s_add_u32 s38, s38, 0x100800
	s_addc_u32 s39, s39, 0
	global_load_dword v133, v111, s[38:39]
	s_add_u32 s38, s38, 0x100800
	s_addc_u32 s39, s39, 0
	global_load_dword v134, v111, s[38:39]
	s_add_u32 s38, s38, 0x100800
	s_addc_u32 s39, s39, 0
	global_load_dword v135, v111, s[38:39]
	s_add_u32 s38, s38, 0x100800
	s_addc_u32 s39, s39, 0
	global_load_dword v136, v111, s[38:39]
	s_add_u32 s38, s38, 0x100800
	s_addc_u32 s39, s39, 0
	global_load_dword v137, v111, s[38:39]
	s_add_u32 s38, s38, 0x100800
	s_addc_u32 s39, s39, 0
	global_load_dword v138, v111, s[38:39]
	s_add_u32 s38, s38, 0x100800
	s_addc_u32 s39, s39, 0
	global_load_dword v139, v111, s[38:39]
	s_add_u32 s38, s38, 0x100800
	s_addc_u32 s39, s39, 0
	global_load_dword v140, v111, s[38:39]
	s_add_u32 s38, s38, 0x100800
	s_addc_u32 s39, s39, 0
	global_load_dword v141, v111, s[38:39]
	s_add_u32 s38, s38, 0x100800
	s_addc_u32 s39, s39, 0
	global_load_dword v142, v111, s[38:39]
	s_add_u32 s38, s38, 0x100800
	s_addc_u32 s39, s39, 0
	global_load_dword v143, v111, s[38:39]
	s_branch .LBB0_90

; __device__ void phase1(const Params& p, LAS unsigned char* lds) {
;     ...
;         for (int i = tid; i < 16384; i += 512) { const int j = i & 15, k = i >> 4; WgT[j * 1024 + k] = p.in_w[(size_t)k * 8208 + 5120 + j]; }
.LBB0_95:
	s_or_b64 exec, exec, s[30:31]
	s_and_saveexec_b64 s[30:31], s[4:5]
	s_cbranch_execz .LBB0_107
	s_mov_b64 s[82:83], -1
	v_mov_b32_e32 v0, v32
	s_and_saveexec_b64 s[80:81], s[18:19]
	s_cbranch_execz .LBB0_104
	v_mov_b64_e32 v[0:1], v[32:33]
	s_and_saveexec_b64 s[82:83], s[20:21]
	s_cbranch_execz .LBB0_101
	s_mov_b64 s[84:85], 0
	v_mov_b32_e32 v2, v103
	v_mov_b64_e32 v[0:1], v[32:33]
	s_waitcnt vmcnt(31)
	ds_write_b32 v110, v112 offset:16384
	s_waitcnt vmcnt(30)
	ds_write_b32 v110, v113 offset:16512
	s_waitcnt vmcnt(29)
	ds_write_b32 v110, v114 offset:16640
	s_waitcnt vmcnt(28)
	ds_write_b32 v110, v115 offset:16768
	s_waitcnt vmcnt(27)
	ds_write_b32 v110, v116 offset:16896
	s_waitcnt vmcnt(26)
	ds_write_b32 v110, v117 offset:17024
	s_waitcnt vmcnt(25)
	ds_write_b32 v110, v118 offset:17152
	s_waitcnt vmcnt(24)
	ds_write_b32 v110, v119 offset:17280
	s_waitcnt vmcnt(23)
	ds_write_b32 v110, v120 offset:17408
	s_waitcnt vmcnt(22)
	ds_write_b32 v110, v121 offset:17536
	s_waitcnt vmcnt(21)
	ds_write_b32 v110, v122 offset:17664
	s_waitcnt vmcnt(20)
	ds_write_b32 v110, v123 offset:17792
	s_waitcnt vmcnt(19)
	ds_write_b32 v110, v124 offset:17920
	s_waitcnt vmcnt(18)
	ds_write_b32 v110, v125 offset:18048
	s_waitcnt vmcnt(17)
	ds_write_b32 v110, v126 offset:18176
	s_waitcnt vmcnt(16)
	ds_write_b32 v110, v127 offset:18304
	s_waitcnt vmcnt(15)
	ds_write_b32 v110, v128 offset:18432
	s_waitcnt vmcnt(14)
	ds_write_b32 v110, v129 offset:18560
	s_waitcnt vmcnt(13)
	ds_write_b32 v110, v130 offset:18688
	s_waitcnt vmcnt(12)
	ds_write_b32 v110, v131 offset:18816
	s_waitcnt vmcnt(11)
	ds_write_b32 v110, v132 offset:18944
	s_waitcnt vmcnt(10)
	ds_write_b32 v110, v133 offset:19072
	s_waitcnt vmcnt(9)
	ds_write_b32 v110, v134 offset:19200
	s_waitcnt vmcnt(8)
	ds_write_b32 v110, v135 offset:19328
	s_waitcnt vmcnt(7)
	ds_write_b32 v110, v136 offset:19456
	s_waitcnt vmcnt(6)
	ds_write_b32 v110, v137 offset:19584
	s_waitcnt vmcnt(5)
	ds_write_b32 v110, v138 offset:19712
	s_waitcnt vmcnt(4)
	ds_write_b32 v110, v139 offset:19840
	s_waitcnt vmcnt(3)
	ds_write_b32 v110, v140 offset:19968
	s_waitcnt vmcnt(2)
	ds_write_b32 v110, v141 offset:20096
	s_waitcnt vmcnt(1)
	ds_write_b32 v110, v142 offset:20224
	s_waitcnt vmcnt(0)
	ds_write_b32 v110, v143 offset:20352
	s_or_b64 exec, exec, s[84:85]

; __device__ __forceinline__ float dot4(const f32x4 a, const f32x4 b) { return (a[0] * b[0] + a[1] * b[1]) + (a[2] * b[2] + a[3] * b[3]); }
; __device__ __forceinline__ void norm_rows2(const f32x4 (&xa)[4], const f32x4 (&xb)[4], const LAS float* gsa, const LAS float* sha, const LAS float* gsb, const LAS float* shb, const LAS float* WgT, ...
;     float ssa = 0.f, ssb = 0.f;
; #pragma unroll
;     for (int i = 0; i < 4; ++i) { ssa += dot4(xa[i], xa[i]); ssb += dot4(xb[i], xb[i]); }
;     ssa = wave_sum(ssa); ssb = wave_sum(ssb);
;     const float ra = rsqrtf(ssa * (1.0f / 1024.0f) + 1e-6f), rb = rsqrtf(ssb * (1.0f / 1024.0f) + 1e-6f);
; __device__ void phase1(const Params& p, LAS unsigned char* lds) {
;     ...
;             const int ra_ = pr < 4 ? rbase + 2 * pr : rbase + 7;
;             const float* xa_ = p.x + (size_t)ra_ * 1024; const float* xb_ = pr < 4 ? xa_ + 1024 : p.ctx + (size_t)crow * 1024;
;             f32x4 xa[4], xb[4];
; #pragma unroll
;             for (int i = 0; i < 4; ++i) { xa[i] = __builtin_nontemporal_load((const f32x4*)(xa_ + i * 256 + lane * 4)); xb[i] = __builtin_nontemporal_load((const f32x4*)(xb_ + i * 256 + lane * 4)); }
.LBB0_110:
	s_add_i32 s28, 0, 0x2000
	s_add_i32 s29, 0, 0x3000
	s_add_i32 s30, 0, 0x1000
	s_cmp_eq_u32 s82, 8
	v_add_u32_e32 v0, s82, v105
	s_cselect_b64 vcc, -1, 0
	v_cndmask_b32_e32 v60, v0, v108, vcc
	v_ashrrev_i32_e32 v61, 31, v60
	v_lshlrev_b64 v[0:1], 12, v[60:61]
	v_lshl_add_u64 v[0:1], s[36:37], 0, v[0:1]
	v_mov_b32_e32 v49, v35
	s_waitcnt lgkmcnt(0)
	v_lshl_add_u64 v[2:3], v[0:1], 0, v[48:49]
	s_mov_b64 s[38:39], 0x1000
	global_load_dwordx4 v[24:27], v[2:3], off nt
	global_load_dwordx4 v[20:23], v[2:3], off offset:1024 nt
	global_load_dwordx4 v[4:7], v[2:3], off offset:3072 nt
	global_load_dwordx4 v[12:15], v[2:3], off offset:2048 nt
	v_lshl_add_u64 v[0:1], v[0:1], 0, s[38:39]
	v_cndmask_b32_e32 v1, v1, v59, vcc
	v_cndmask_b32_e32 v0, v0, v58, vcc
	v_lshl_add_u64 v[8:9], v[0:1], 0, v[48:49]
	global_load_dwordx4 v[28:31], v[8:9], off nt
	global_load_dwordx4 v[16:19], v[8:9], off offset:1024 nt
	global_load_dwordx4 v[0:3], v[8:9], off offset:3072 nt
	s_nop 0
	global_load_dwordx4 v[8:11], v[8:9], off offset:2048 nt
	s_and_b64 s[38:39], vcc, exec
	s_cselect_b32 s28, s28, 0
	s_cselect_b32 s29, s29, s30
	s_waitcnt vmcnt(7)
	v_pk_mul_f32 v[62:63], v[26:27], v[26:27]
	v_pk_mul_f32 v[64:65], v[24:25], v[24:25]
	s_waitcnt vmcnt(6)
	v_pk_mul_f32 v[66:67], v[22:23], v[22:23]
	v_pk_mul_f32 v[68:69], v[20:21], v[20:21]
	s_waitcnt vmcnt(4)
	v_mul_f32_e32 v70, v15, v15
	v_pk_mov_b32 v[72:73], v[64:65], v[62:63] op_sel:[1,0]
	v_mov_b32_e32 v65, v63
	v_pk_mov_b32 v[62:63], v[68:69], v[66:67] op_sel:[1,0]
	v_mov_b32_e32 v69, v67
	v_mul_f32_e32 v80, v7, v7
	v_mul_f32_e32 v34, v13, v13
	v_pk_fma_f32 v[70:71], v[14:15], v[14:15], v[70:71] op_sel_hi:[1,1,0]
	v_pk_add_f32 v[64:65], v[72:73], v[64:65]
	s_waitcnt vmcnt(3)
	v_pk_mul_f32 v[72:73], v[30:31], v[30:31]
	v_pk_mul_f32 v[74:75], v[28:29], v[28:29]
	v_pk_add_f32 v[62:63], v[62:63], v[68:69]
	s_waitcnt vmcnt(2)
	v_pk_mul_f32 v[68:69], v[18:19], v[18:19]
	v_pk_mul_f32 v[76:77], v[16:17], v[16:17]
	v_mul_f32_e32 v49, v4, v4
	v_mul_f32_e32 v79, v5, v5
	v_mul_f32_e32 v78, v6, v6
	v_pk_fma_f32 v[66:67], v[12:13], v[12:13], v[34:35] op_sel_hi:[1,1,0]
	v_mov_b32_e32 v71, v80
	v_pk_mov_b32 v[80:81], v[74:75], v[72:73] op_sel:[1,0]
	v_mov_b32_e32 v75, v73
	v_pk_mov_b32 v[72:73], v[76:77], v[68:69] op_sel:[1,0]
	v_mov_b32_e32 v77, v69
	v_pk_add_f32 v[64:65], v[64:65], v[64:65] op_sel:[0,1] op_sel_hi:[1,0]
	v_pk_add_f32 v[62:63], v[62:63], v[62:63] op_sel:[0,1] op_sel_hi:[1,0]
	v_mov_b32_e32 v67, v78
	s_waitcnt vmcnt(0)
	v_mul_f32_e32 v34, v9, v9
	v_mul_f32_e32 v78, v11, v11
	v_pk_add_f32 v[74:75], v[80:81], v[74:75]
	v_pk_add_f32 v[72:73], v[72:73], v[76:77]
	v_mov_b32_e32 v65, v49
	v_mov_b32_e32 v63, v79
	v_mul_f32_e32 v82, v0, v0
	v_mul_f32_e32 v83, v1, v1
	v_mul_f32_e32 v84, v2, v2
	v_mul_f32_e32 v85, v3, v3
	v_pk_add_f32 v[66:67], v[66:67], v[70:71]
	v_pk_fma_f32 v[68:69], v[8:9], v[8:9], v[34:35] op_sel_hi:[1,1,0]
	v_pk_fma_f32 v[70:71], v[10:11], v[10:11], v[78:79] op_sel_hi:[1,1,0]
	v_pk_add_f32 v[62:63], v[64:65], v[62:63]
	v_pk_add_f32 v[64:65], v[74:75], v[74:75] op_sel:[0,1] op_sel_hi:[1,0]
	v_pk_add_f32 v[72:73], v[72:73], v[72:73] op_sel:[0,1] op_sel_hi:[1,0]
	v_mov_b32_e32 v69, v84
	v_mov_b32_e32 v71, v85
	v_mov_b32_e32 v65, v82
	v_mov_b32_e32 v73, v83
	v_pk_add_f32 v[68:69], v[68:69], v[70:71]
	v_pk_add_f32 v[64:65], v[64:65], v[72:73]
	v_pk_add_f32 v[62:63], v[62:63], v[66:67]
	v_pk_add_f32 v[64:65], v[64:65], v[68:69]
	v_mov_b32_e32 v67, v62
	v_mov_b32_e32 v66, v64
	v_mov_b32_e32 v62, v65
	v_pk_add_f32 v[62:63], v[66:67], v[62:63]
	v_lshlrev_b64 v[76:77], 11, v[60:61]
	v_add_u32_e32 v49, s28, v48
	v_add_u32_e32 v61, s29, v48
	v_add_u32_e32 v34, 1, v60
	ds_read_b128 v[64:67], v99
	ds_read_b128 v[68:71], v99 offset:4096
	ds_read_b128 v[80:83], v49
	ds_read_b128 v[84:87], v61
	v_add_f32_dpp v62, v62, v62 row_mirror row_mask:0xf bank_mask:0xf
	v_add_f32_dpp v63, v63, v63 row_mirror row_mask:0xf bank_mask:0xf
	v_cndmask_b32_e32 v74, v34, v109, vcc
	v_add_f32_dpp v62, v62, v62 row_half_mirror row_mask:0xf bank_mask:0xf
	v_add_f32_dpp v63, v63, v63 row_half_mirror row_mask:0xf bank_mask:0xf
	v_ashrrev_i32_e32 v75, 31, v74
	v_add_f32_dpp v62, v62, v62 quad_perm:[1,0,3,2] row_mask:0xf bank_mask:0xf
	v_add_f32_dpp v63, v63, v63 quad_perm:[1,0,3,2] row_mask:0xf bank_mask:0xf
	v_lshlrev_b64 v[74:75], 11, v[74:75]
	v_add_f32_dpp v62, v62, v62 quad_perm:[2,3,0,1] row_mask:0xf bank_mask:0xf
	v_add_f32_dpp v63, v63, v63 quad_perm:[2,3,0,1] row_mask:0xf bank_mask:0xf
	v_lshl_add_u64 v[78:79], v[36:37], 0, v[76:77]
	s_nop 0
	v_readlane_b32 s54, v62, 0
	v_readlane_b32 s55, v62, 16
	v_readlane_b32 s56, v62, 32
	v_readlane_b32 s57, v62, 48
	v_readlane_b32 s58, v63, 0
	v_readlane_b32 s59, v63, 16
	v_readlane_b32 s60, v63, 32
	v_readlane_b32 s61, v63, 48
	v_mov_b32_e32 v62, s54
	v_mov_b32_e32 v63, s58
	v_add_f32_e32 v62, s55, v62
	v_add_f32_e32 v63, s59, v63
	v_add_f32_e32 v62, s56, v62
	v_add_f32_e32 v63, s60, v63
	v_add_f32_e32 v62, s57, v62
	v_add_f32_e32 v63, s61, v63
	s_waitcnt lgkmcnt(0)
; #define LAS __attribute__((address_space(3)))
; __device__ __forceinline__ unsigned cvt_pk_bf16(float lo, float hi) { unsigned r; asm volatile("v_cvt_pk_bf16_f32 %0, %1, %2" : "=v"(r) : "v"(lo), "v"(hi)); return r; }
; __device__ __forceinline__ float dot4(const f32x4 a, const f32x4 b) { return (a[0] * b[0] + a[1] * b[1]) + (a[2] * b[2] + a[3] * b[3]); }
; __device__ __forceinline__ void norm_rows2(const f32x4 (&xa)[4], const f32x4 (&xb)[4], const LAS float* gsa, const LAS float* sha, const LAS float* gsb, const LAS float* shb, const LAS float* WgT, ...
;     ...
;     ssa = wave_sum(ssa); ssb = wave_sum(ssb);
;     const float ra = rsqrtf(ssa * (1.0f / 1024.0f) + 1e-6f), rb = rsqrtf(ssb * (1.0f / 1024.0f) + 1e-6f);
;     f32x4 ya[4], yb[4];
; #pragma unroll
;     for (int i = 0; i < 4; ++i) {
;         ya[i] = xa[i] * ra * *(const LAS f32x4*)(gsa + i * 256 + lane * 4) + *(const LAS f32x4*)(sha + i * 256 + lane * 4);
;         yb[i] = xb[i] * rb * *(const LAS f32x4*)(gsb + i * 256 + lane * 4) + *(const LAS f32x4*)(shb + i * 256 + lane * 4);
;         u32x2 w; w.x = cvt_pk_bf16(ya[i][0], ya[i][1]); w.y = cvt_pk_bf16(ya[i][2], ya[i][3]); *(u32x2*)(oa + i * 256 + lane * 4) = w;
;         u32x2 v; v.x = cvt_pk_bf16(yb[i][0], yb[i][1]); v.y = cvt_pk_bf16(yb[i][2], yb[i][3]); *(u32x2*)(ob + i * 256 + lane * 4) = v; }
;     f32x4 pa[4], pb[4];
; #pragma unroll
;     for (int jq = 0; jq < 4; ++jq) { f32x4 sa = (f32x4){0.f, 0.f, 0.f, 0.f}, sb = sa;
; #pragma unroll
;         for (int i = 0; i < 4; ++i) { const LAS float* wp = WgT + (jq * 4) * 1024 + i * 256 + lane * 4;
;             const f32x4 w0 = *(const LAS f32x4*)wp, w1 = *(const LAS f32x4*)(wp + 1024), w2 = *(const LAS f32x4*)(wp + 2048), w3 = *(const LAS f32x4*)(wp + 3072);
;             sa += (f32x4){dot4(ya[i], w0), dot4(ya[i], w1), dot4(ya[i], w2), dot4(ya[i], w3)};
;             sb += (f32x4){dot4(yb[i], w0), dot4(yb[i], w1), dot4(yb[i], w2), dot4(yb[i], w3)}; }
	s_nop 0
	v_pk_fma_f32 v[62:63], v[62:63], s[46:47], v[50:51] op_sel_hi:[1,0,0]
	s_nop 0
	v_mul_f32_e32 v72, 0x4b800000, v63
	v_cmp_gt_f32_e64 s[28:29], s34, v63
	v_mul_f32_e32 v73, 0x4b800000, v62
	v_cmp_gt_f32_e64 s[30:31], s34, v62
	v_cndmask_b32_e64 v63, v63, v72, s[28:29]
	v_rsq_f32_e32 v72, v63
	v_cndmask_b32_e64 v62, v62, v73, s[30:31]
	v_rsq_f32_e32 v73, v62
	v_lshl_add_u64 v[62:63], v[36:37], 0, v[74:75]
	v_mul_f32_e32 v74, 0x45800000, v72
	v_cndmask_b32_e64 v88, v72, v74, s[28:29]
	v_mul_f32_e32 v75, 0x45800000, v73
	v_cndmask_b32_e64 v90, v73, v75, s[30:31]
	v_pk_mul_f32 v[24:25], v[24:25], v[88:89] op_sel_hi:[1,0]
	v_pk_mul_f32 v[26:27], v[26:27], v[88:89] op_sel_hi:[1,0]
	v_pk_mul_f32 v[28:29], v[28:29], v[90:91] op_sel_hi:[1,0]
	v_pk_mul_f32 v[30:31], v[30:31], v[90:91] op_sel_hi:[1,0]
	v_pk_mul_f32 v[92:93], v[20:21], v[88:89] op_sel_hi:[1,0]
	v_pk_fma_f32 v[74:75], v[66:67], v[26:27], v[70:71]
	v_pk_fma_f32 v[76:77], v[64:65], v[24:25], v[68:69]
	v_pk_mul_f32 v[110:111], v[22:23], v[88:89] op_sel_hi:[1,0]
	v_cvt_pk_bf16_f32 v20, v76, v77
	v_cvt_pk_bf16_f32 v21, v74, v75
	v_pk_fma_f32 v[70:71], v[82:83], v[30:31], v[86:87]
	v_pk_fma_f32 v[72:73], v[80:81], v[28:29], v[84:85]
	global_store_dwordx2 v[78:79], v[20:21], off
	v_cvt_pk_bf16_f32 v64, v72, v73
	v_cvt_pk_bf16_f32 v65, v70, v71
	ds_read_b128 v[20:23], v99 offset:1024
	ds_read_b128 v[24:27], v99 offset:5120
	ds_read_b128 v[28:31], v49 offset:1024
	ds_read_b128 v[80:83], v61 offset:1024
	v_pk_mul_f32 v[16:17], v[16:17], v[90:91] op_sel_hi:[1,0]
	global_store_dwordx2 v[62:63], v[64:65], off
	v_pk_mul_f32 v[18:19], v[18:19], v[90:91] op_sel_hi:[1,0]
	s_waitcnt lgkmcnt(2)
	v_pk_fma_f32 v[66:67], v[110:111], v[22:23], v[26:27]
	v_pk_fma_f32 v[68:69], v[92:93], v[20:21], v[24:25]
	s_waitcnt lgkmcnt(0)
	v_pk_fma_f32 v[64:65], v[16:17], v[28:29], v[80:81]
	v_cvt_pk_bf16_f32 v16, v68, v69
	v_cvt_pk_bf16_f32 v17, v66, v67
	v_pk_fma_f32 v[30:31], v[18:19], v[30:31], v[82:83]
	global_store_dwordx2 v[78:79], v[16:17], off offset:512
	v_cvt_pk_bf16_f32 v16, v64, v65
	v_cvt_pk_bf16_f32 v17, v30, v31
	global_store_dwordx2 v[62:63], v[16:17], off offset:512
	ds_read_b128 v[16:19], v99 offset:2048
	ds_read_b128 v[20:23], v99 offset:6144
	ds_read_b128 v[24:27], v49 offset:2048
	ds_read_b128 v[80:83], v61 offset:2048
	v_pk_mul_f32 v[12:13], v[12:13], v[88:89] op_sel_hi:[1,0]
	v_pk_mul_f32 v[14:15], v[14:15], v[88:89] op_sel_hi:[1,0]
	v_pk_mul_f32 v[8:9], v[8:9], v[90:91] op_sel_hi:[1,0]
	s_waitcnt lgkmcnt(2)
	v_pk_fma_f32 v[14:15], v[14:15], v[18:19], v[22:23]
	v_pk_fma_f32 v[18:19], v[12:13], v[16:17], v[20:21]
	v_pk_mul_f32 v[10:11], v[10:11], v[90:91] op_sel_hi:[1,0]
	s_waitcnt lgkmcnt(0)
	v_pk_fma_f32 v[20:21], v[8:9], v[24:25], v[80:81]
	v_cvt_pk_bf16_f32 v8, v18, v19
	v_cvt_pk_bf16_f32 v9, v14, v15
	v_pk_fma_f32 v[16:17], v[10:11], v[26:27], v[82:83]
	global_store_dwordx2 v[78:79], v[8:9], off offset:1024
	v_cvt_pk_bf16_f32 v8, v20, v21
	v_cvt_pk_bf16_f32 v9, v16, v17
	global_store_dwordx2 v[62:63], v[8:9], off offset:1024
	ds_read_b128 v[8:11], v99 offset:3072
	ds_read_b128 v[22:25], v99 offset:7168
	v_pk_mul_f32 v[12:13], v[4:5], v[88:89] op_sel_hi:[1,0]
	v_pk_mul_f32 v[80:81], v[6:7], v[88:89] op_sel_hi:[1,0]
	ds_read_b128 v[4:7], v49 offset:3072
	ds_read_b128 v[26:29], v61 offset:3072
	v_pk_mul_f32 v[0:1], v[0:1], v[90:91] op_sel_hi:[1,0]
	s_waitcnt lgkmcnt(2)
	v_pk_fma_f32 v[10:11], v[80:81], v[10:11], v[24:25]
	v_pk_fma_f32 v[12:13], v[12:13], v[8:9], v[22:23]
	v_pk_mul_f32 v[2:3], v[2:3], v[90:91] op_sel_hi:[1,0]
	s_waitcnt lgkmcnt(0)
	v_pk_fma_f32 v[8:9], v[0:1], v[4:5], v[26:27]
	v_cvt_pk_bf16_f32 v0, v12, v13
	v_cvt_pk_bf16_f32 v1, v10, v11
	v_pk_fma_f32 v[6:7], v[2:3], v[6:7], v[28:29]
	global_store_dwordx2 v[78:79], v[0:1], off offset:1536
	v_cvt_pk_bf16_f32 v4, v8, v9
	v_cvt_pk_bf16_f32 v5, v6, v7
	global_store_dwordx2 v[62:63], v[4:5], off offset:1536
	ds_read_b128 v[110:113], v99 offset:16384
	ds_read_b128 v[114:117], v99 offset:20480
	ds_read_b128 v[118:121], v99 offset:24576
	ds_read_b128 v[122:125], v99 offset:28672
	ds_read_b128 v[126:129], v99 offset:32768
	ds_read_b128 v[130:133], v99 offset:36864
	ds_read_b128 v[134:137], v99 offset:40960
	ds_read_b128 v[138:141], v99 offset:45056
	ds_read_b128 v[142:145], v99 offset:49152
	ds_read_b128 v[146:149], v99 offset:53248
	ds_read_b128 v[150:153], v99 offset:57344
	ds_read_b128 v[154:157], v99 offset:61440
	s_waitcnt lgkmcnt(8)
	v_pk_mul_f32 v[160:161], v[72:73], v[110:111]
	v_pk_mul_f32 v[192:193], v[76:77], v[110:111]
	v_pk_mul_f32 v[162:163], v[72:73], v[114:115]
	v_pk_mul_f32 v[194:195], v[76:77], v[114:115]
	v_pk_mul_f32 v[164:165], v[72:73], v[118:119]
	v_pk_mul_f32 v[196:197], v[76:77], v[118:119]
	v_pk_mul_f32 v[166:167], v[72:73], v[122:123]
	v_pk_mul_f32 v[198:199], v[76:77], v[122:123]
	v_pk_fma_f32 v[160:161], v[70:71], v[112:113], v[160:161]
	v_pk_fma_f32 v[192:193], v[74:75], v[112:113], v[192:193]
	v_pk_fma_f32 v[162:163], v[70:71], v[116:117], v[162:163]
	v_pk_fma_f32 v[194:195], v[74:75], v[116:117], v[194:195]
	v_pk_fma_f32 v[164:165], v[70:71], v[120:121], v[164:165]
	v_pk_fma_f32 v[196:197], v[74:75], v[120:121], v[196:197]
	v_pk_fma_f32 v[166:167], v[70:71], v[124:125], v[166:167]
	v_pk_fma_f32 v[198:199], v[74:75], v[124:125], v[198:199]
	ds_read_b128 v[228:231], v100 offset:49152
	ds_read_b128 v[232:235], v100 offset:53248
	ds_read_b128 v[236:239], v100 offset:57344
	ds_read_b128 v[240:243], v100 offset:61440
	s_waitcnt lgkmcnt(8)
; #define LAS __attribute__((address_space(3)))
; __device__ __forceinline__ float dot4(const f32x4 a, const f32x4 b) { return (a[0] * b[0] + a[1] * b[1]) + (a[2] * b[2] + a[3] * b[3]); }
; __device__ __forceinline__ void norm_rows2(const f32x4 (&xa)[4], const f32x4 (&xb)[4], const LAS float* gsa, const LAS float* sha, const LAS float* gsb, const LAS float* shb, const LAS float* WgT, ...
;     ...
;     for (int jq = 0; jq < 4; ++jq) { f32x4 sa = (f32x4){0.f, 0.f, 0.f, 0.f}, sb = sa;
; #pragma unroll
;         for (int i = 0; i < 4; ++i) { const LAS float* wp = WgT + (jq * 4) * 1024 + i * 256 + lane * 4;
;             const f32x4 w0 = *(const LAS f32x4*)wp, w1 = *(const LAS f32x4*)(wp + 1024), w2 = *(const LAS f32x4*)(wp + 2048), w3 = *(const LAS f32x4*)(wp + 3072);
;             sa += (f32x4){dot4(ya[i], w0), dot4(ya[i], w1), dot4(ya[i], w2), dot4(ya[i], w3)};
;             sb += (f32x4){dot4(yb[i], w0), dot4(yb[i], w1), dot4(yb[i], w2), dot4(yb[i], w3)}; }
;         pa[jq] = sa; pb[jq] = sb; }
	v_pk_mul_f32 v[168:169], v[72:73], v[126:127]
	v_pk_mul_f32 v[200:201], v[76:77], v[126:127]
	v_pk_mul_f32 v[170:171], v[72:73], v[130:131]
	v_pk_mul_f32 v[202:203], v[76:77], v[130:131]
	v_pk_mul_f32 v[172:173], v[72:73], v[134:135]
	v_pk_mul_f32 v[204:205], v[76:77], v[134:135]
	v_pk_mul_f32 v[174:175], v[72:73], v[138:139]
	v_pk_mul_f32 v[206:207], v[76:77], v[138:139]
	v_pk_fma_f32 v[168:169], v[70:71], v[128:129], v[168:169]
	v_pk_fma_f32 v[200:201], v[74:75], v[128:129], v[200:201]
	v_pk_fma_f32 v[170:171], v[70:71], v[132:133], v[170:171]
	v_pk_fma_f32 v[202:203], v[74:75], v[132:133], v[202:203]
	v_pk_fma_f32 v[172:173], v[70:71], v[136:137], v[172:173]
	v_pk_fma_f32 v[204:205], v[74:75], v[136:137], v[204:205]
	v_pk_fma_f32 v[174:175], v[70:71], v[140:141], v[174:175]
	v_pk_fma_f32 v[206:207], v[74:75], v[140:141], v[206:207]
	ds_read_b128 v[110:113], v99 offset:17408
	ds_read_b128 v[114:117], v99 offset:21504
	ds_read_b128 v[118:121], v99 offset:25600
	ds_read_b128 v[122:125], v99 offset:29696
	s_waitcnt lgkmcnt(8)
	v_pk_mul_f32 v[176:177], v[72:73], v[142:143]
	v_pk_mul_f32 v[208:209], v[76:77], v[142:143]
	v_pk_mul_f32 v[178:179], v[72:73], v[146:147]
	v_pk_mul_f32 v[210:211], v[76:77], v[146:147]
	v_pk_mul_f32 v[180:181], v[72:73], v[150:151]
	v_pk_mul_f32 v[212:213], v[76:77], v[150:151]
	v_pk_mul_f32 v[182:183], v[72:73], v[154:155]
	v_pk_mul_f32 v[214:215], v[76:77], v[154:155]
	v_pk_fma_f32 v[176:177], v[70:71], v[144:145], v[176:177]
	v_pk_fma_f32 v[208:209], v[74:75], v[144:145], v[208:209]
	v_pk_fma_f32 v[178:179], v[70:71], v[148:149], v[178:179]
	v_pk_fma_f32 v[210:211], v[74:75], v[148:149], v[210:211]
	v_pk_fma_f32 v[180:181], v[70:71], v[152:153], v[180:181]
	v_pk_fma_f32 v[212:213], v[74:75], v[152:153], v[212:213]
	v_pk_fma_f32 v[182:183], v[70:71], v[156:157], v[182:183]
	v_pk_fma_f32 v[214:215], v[74:75], v[156:157], v[214:215]
	ds_read_b128 v[126:129], v99 offset:33792
	ds_read_b128 v[130:133], v99 offset:37888
	ds_read_b128 v[134:137], v99 offset:41984
	ds_read_b128 v[138:141], v99 offset:46080
	s_waitcnt lgkmcnt(8)
	v_pk_mul_f32 v[184:185], v[72:73], v[228:229]
	v_pk_mul_f32 v[216:217], v[76:77], v[228:229]
	v_pk_mul_f32 v[186:187], v[72:73], v[232:233]
	v_pk_mul_f32 v[218:219], v[76:77], v[232:233]
	v_pk_mul_f32 v[188:189], v[72:73], v[236:237]
	v_pk_mul_f32 v[220:221], v[76:77], v[236:237]
	v_pk_mul_f32 v[190:191], v[72:73], v[240:241]
	v_pk_mul_f32 v[222:223], v[76:77], v[240:241]
	v_pk_fma_f32 v[184:185], v[70:71], v[230:231], v[184:185]
	v_pk_fma_f32 v[216:217], v[74:75], v[230:231], v[216:217]
	v_pk_fma_f32 v[186:187], v[70:71], v[234:235], v[186:187]
	v_pk_fma_f32 v[218:219], v[74:75], v[234:235], v[218:219]
	v_pk_fma_f32 v[188:189], v[70:71], v[238:239], v[188:189]
	v_pk_fma_f32 v[220:221], v[74:75], v[238:239], v[220:221]
	v_pk_fma_f32 v[190:191], v[70:71], v[242:243], v[190:191]
	v_pk_fma_f32 v[222:223], v[74:75], v[242:243], v[222:223]
	ds_read_b128 v[142:145], v99 offset:50176
	ds_read_b128 v[146:149], v99 offset:54272
	ds_read_b128 v[150:153], v99 offset:58368
	ds_read_b128 v[154:157], v99 offset:62464
	s_waitcnt lgkmcnt(8)
	v_pk_fma_f32 v[160:161], v[64:65], v[110:111], v[160:161]
	v_pk_fma_f32 v[192:193], v[68:69], v[110:111], v[192:193]
	v_pk_fma_f32 v[162:163], v[64:65], v[114:115], v[162:163]
	v_pk_fma_f32 v[194:195], v[68:69], v[114:115], v[194:195]
	v_pk_fma_f32 v[164:165], v[64:65], v[118:119], v[164:165]
	v_pk_fma_f32 v[196:197], v[68:69], v[118:119], v[196:197]
	v_pk_fma_f32 v[166:167], v[64:65], v[122:123], v[166:167]
	v_pk_fma_f32 v[198:199], v[68:69], v[122:123], v[198:199]
	v_pk_fma_f32 v[160:161], v[30:31], v[112:113], v[160:161]
	v_pk_fma_f32 v[192:193], v[66:67], v[112:113], v[192:193]
	v_pk_fma_f32 v[162:163], v[30:31], v[116:117], v[162:163]
	v_pk_fma_f32 v[194:195], v[66:67], v[116:117], v[194:195]
	v_pk_fma_f32 v[164:165], v[30:31], v[120:121], v[164:165]
	v_pk_fma_f32 v[196:197], v[66:67], v[120:121], v[196:197]
	v_pk_fma_f32 v[166:167], v[30:31], v[124:125], v[166:167]
	v_pk_fma_f32 v[198:199], v[66:67], v[124:125], v[198:199]
	ds_read_b128 v[228:231], v100 offset:50176
	ds_read_b128 v[232:235], v100 offset:54272
	ds_read_b128 v[236:239], v100 offset:58368
	ds_read_b128 v[240:243], v100 offset:62464
	s_waitcnt lgkmcnt(8)
	v_pk_fma_f32 v[168:169], v[64:65], v[126:127], v[168:169]
	v_pk_fma_f32 v[200:201], v[68:69], v[126:127], v[200:201]
	v_pk_fma_f32 v[170:171], v[64:65], v[130:131], v[170:171]
	v_pk_fma_f32 v[202:203], v[68:69], v[130:131], v[202:203]
	v_pk_fma_f32 v[172:173], v[64:65], v[134:135], v[172:173]
	v_pk_fma_f32 v[204:205], v[68:69], v[134:135], v[204:205]
	v_pk_fma_f32 v[174:175], v[64:65], v[138:139], v[174:175]
	v_pk_fma_f32 v[206:207], v[68:69], v[138:139], v[206:207]
	v_pk_fma_f32 v[168:169], v[30:31], v[128:129], v[168:169]
	v_pk_fma_f32 v[200:201], v[66:67], v[128:129], v[200:201]
	v_pk_fma_f32 v[170:171], v[30:31], v[132:133], v[170:171]
	v_pk_fma_f32 v[202:203], v[66:67], v[132:133], v[202:203]
	v_pk_fma_f32 v[172:173], v[30:31], v[136:137], v[172:173]
	v_pk_fma_f32 v[204:205], v[66:67], v[136:137], v[204:205]
	v_pk_fma_f32 v[174:175], v[30:31], v[140:141], v[174:175]
	v_pk_fma_f32 v[206:207], v[66:67], v[140:141], v[206:207]
	ds_read_b128 v[110:113], v99 offset:18432
	ds_read_b128 v[114:117], v99 offset:22528
	ds_read_b128 v[118:121], v99 offset:26624
	ds_read_b128 v[122:125], v99 offset:30720
	s_waitcnt lgkmcnt(8)
; #define LAS __attribute__((address_space(3)))
; __device__ __forceinline__ float dot4(const f32x4 a, const f32x4 b) { return (a[0] * b[0] + a[1] * b[1]) + (a[2] * b[2] + a[3] * b[3]); }
; __device__ __forceinline__ void norm_rows2(const f32x4 (&xa)[4], const f32x4 (&xb)[4], const LAS float* gsa, const LAS float* sha, const LAS float* gsb, const LAS float* shb, const LAS float* WgT, ...
;     ...
;     for (int jq = 0; jq < 4; ++jq) { f32x4 sa = (f32x4){0.f, 0.f, 0.f, 0.f}, sb = sa;
; #pragma unroll
;         for (int i = 0; i < 4; ++i) { const LAS float* wp = WgT + (jq * 4) * 1024 + i * 256 + lane * 4;
;             const f32x4 w0 = *(const LAS f32x4*)wp, w1 = *(const LAS f32x4*)(wp + 1024), w2 = *(const LAS f32x4*)(wp + 2048), w3 = *(const LAS f32x4*)(wp + 3072);
;             sa += (f32x4){dot4(ya[i], w0), dot4(ya[i], w1), dot4(ya[i], w2), dot4(ya[i], w3)};
;             sb += (f32x4){dot4(yb[i], w0), dot4(yb[i], w1), dot4(yb[i], w2), dot4(yb[i], w3)}; }
;         pa[jq] = sa; pb[jq] = sb; }
	v_pk_fma_f32 v[176:177], v[64:65], v[142:143], v[176:177]
	v_pk_fma_f32 v[208:209], v[68:69], v[142:143], v[208:209]
	v_pk_fma_f32 v[178:179], v[64:65], v[146:147], v[178:179]
	v_pk_fma_f32 v[210:211], v[68:69], v[146:147], v[210:211]
	v_pk_fma_f32 v[180:181], v[64:65], v[150:151], v[180:181]
	v_pk_fma_f32 v[212:213], v[68:69], v[150:151], v[212:213]
	v_pk_fma_f32 v[182:183], v[64:65], v[154:155], v[182:183]
	v_pk_fma_f32 v[214:215], v[68:69], v[154:155], v[214:215]
	v_pk_fma_f32 v[176:177], v[30:31], v[144:145], v[176:177]
	v_pk_fma_f32 v[208:209], v[66:67], v[144:145], v[208:209]
	v_pk_fma_f32 v[178:179], v[30:31], v[148:149], v[178:179]
	v_pk_fma_f32 v[210:211], v[66:67], v[148:149], v[210:211]
	v_pk_fma_f32 v[180:181], v[30:31], v[152:153], v[180:181]
	v_pk_fma_f32 v[212:213], v[66:67], v[152:153], v[212:213]
	v_pk_fma_f32 v[182:183], v[30:31], v[156:157], v[182:183]
	v_pk_fma_f32 v[214:215], v[66:67], v[156:157], v[214:215]
	ds_read_b128 v[126:129], v99 offset:34816
	ds_read_b128 v[130:133], v99 offset:38912
	ds_read_b128 v[134:137], v99 offset:43008
	ds_read_b128 v[138:141], v99 offset:47104
	s_waitcnt lgkmcnt(8)
	v_pk_fma_f32 v[184:185], v[64:65], v[228:229], v[184:185]
	v_pk_fma_f32 v[216:217], v[68:69], v[228:229], v[216:217]
	v_pk_fma_f32 v[186:187], v[64:65], v[232:233], v[186:187]
	v_pk_fma_f32 v[218:219], v[68:69], v[232:233], v[218:219]
	v_pk_fma_f32 v[188:189], v[64:65], v[236:237], v[188:189]
	v_pk_fma_f32 v[220:221], v[68:69], v[236:237], v[220:221]
	v_pk_fma_f32 v[190:191], v[64:65], v[240:241], v[190:191]
	v_pk_fma_f32 v[222:223], v[68:69], v[240:241], v[222:223]
	v_pk_fma_f32 v[184:185], v[30:31], v[230:231], v[184:185]
	v_pk_fma_f32 v[216:217], v[66:67], v[230:231], v[216:217]
	v_pk_fma_f32 v[186:187], v[30:31], v[234:235], v[186:187]
	v_pk_fma_f32 v[218:219], v[66:67], v[234:235], v[218:219]
	v_pk_fma_f32 v[188:189], v[30:31], v[238:239], v[188:189]
	v_pk_fma_f32 v[220:221], v[66:67], v[238:239], v[220:221]
	v_pk_fma_f32 v[190:191], v[30:31], v[242:243], v[190:191]
	v_pk_fma_f32 v[222:223], v[66:67], v[242:243], v[222:223]
	ds_read_b128 v[142:145], v99 offset:51200
	ds_read_b128 v[146:149], v99 offset:55296
	ds_read_b128 v[150:153], v99 offset:59392
	ds_read_b128 v[154:157], v99 offset:63488
	s_waitcnt lgkmcnt(8)
	v_pk_fma_f32 v[160:161], v[20:21], v[110:111], v[160:161]
	v_pk_fma_f32 v[192:193], v[18:19], v[110:111], v[192:193]
	v_pk_fma_f32 v[162:163], v[20:21], v[114:115], v[162:163]
	v_pk_fma_f32 v[194:195], v[18:19], v[114:115], v[194:195]
	v_pk_fma_f32 v[164:165], v[20:21], v[118:119], v[164:165]
	v_pk_fma_f32 v[196:197], v[18:19], v[118:119], v[196:197]
	v_pk_fma_f32 v[166:167], v[20:21], v[122:123], v[166:167]
	v_pk_fma_f32 v[198:199], v[18:19], v[122:123], v[198:199]
	v_pk_fma_f32 v[160:161], v[16:17], v[112:113], v[160:161]
	v_pk_fma_f32 v[192:193], v[14:15], v[112:113], v[192:193]
	v_pk_fma_f32 v[162:163], v[16:17], v[116:117], v[162:163]
	v_pk_fma_f32 v[194:195], v[14:15], v[116:117], v[194:195]
	v_pk_fma_f32 v[164:165], v[16:17], v[120:121], v[164:165]
	v_pk_fma_f32 v[196:197], v[14:15], v[120:121], v[196:197]
	v_pk_fma_f32 v[166:167], v[16:17], v[124:125], v[166:167]
	v_pk_fma_f32 v[198:199], v[14:15], v[124:125], v[198:199]
	ds_read_b128 v[228:231], v100 offset:51200
	ds_read_b128 v[232:235], v100 offset:55296
	ds_read_b128 v[236:239], v100 offset:59392
	ds_read_b128 v[240:243], v100 offset:63488
	s_waitcnt lgkmcnt(8)
	v_pk_fma_f32 v[168:169], v[20:21], v[126:127], v[168:169]
	v_pk_fma_f32 v[200:201], v[18:19], v[126:127], v[200:201]
	v_pk_fma_f32 v[170:171], v[20:21], v[130:131], v[170:171]
	v_pk_fma_f32 v[202:203], v[18:19], v[130:131], v[202:203]
	v_pk_fma_f32 v[172:173], v[20:21], v[134:135], v[172:173]
	v_pk_fma_f32 v[204:205], v[18:19], v[134:135], v[204:205]
	v_pk_fma_f32 v[174:175], v[20:21], v[138:139], v[174:175]
	v_pk_fma_f32 v[206:207], v[18:19], v[138:139], v[206:207]
	v_pk_fma_f32 v[168:169], v[16:17], v[128:129], v[168:169]
	v_pk_fma_f32 v[200:201], v[14:15], v[128:129], v[200:201]
	v_pk_fma_f32 v[170:171], v[16:17], v[132:133], v[170:171]
	v_pk_fma_f32 v[202:203], v[14:15], v[132:133], v[202:203]
	v_pk_fma_f32 v[172:173], v[16:17], v[136:137], v[172:173]
	v_pk_fma_f32 v[204:205], v[14:15], v[136:137], v[204:205]
	v_pk_fma_f32 v[174:175], v[16:17], v[140:141], v[174:175]
	v_pk_fma_f32 v[206:207], v[14:15], v[140:141], v[206:207]
	ds_read_b128 v[110:113], v99 offset:19456
	ds_read_b128 v[114:117], v99 offset:23552
	ds_read_b128 v[118:121], v99 offset:27648
	ds_read_b128 v[122:125], v99 offset:31744
	s_waitcnt lgkmcnt(8)
	v_pk_fma_f32 v[176:177], v[20:21], v[142:143], v[176:177]
	v_pk_fma_f32 v[208:209], v[18:19], v[142:143], v[208:209]
	v_pk_fma_f32 v[178:179], v[20:21], v[146:147], v[178:179]
	v_pk_fma_f32 v[210:211], v[18:19], v[146:147], v[210:211]
	v_pk_fma_f32 v[180:181], v[20:21], v[150:151], v[180:181]
	v_pk_fma_f32 v[212:213], v[18:19], v[150:151], v[212:213]
	v_pk_fma_f32 v[182:183], v[20:21], v[154:155], v[182:183]
	v_pk_fma_f32 v[214:215], v[18:19], v[154:155], v[214:215]
	v_pk_fma_f32 v[176:177], v[16:17], v[144:145], v[176:177]
	v_pk_fma_f32 v[208:209], v[14:15], v[144:145], v[208:209]
	v_pk_fma_f32 v[178:179], v[16:17], v[148:149], v[178:179]
	v_pk_fma_f32 v[210:211], v[14:15], v[148:149], v[210:211]
	v_pk_fma_f32 v[180:181], v[16:17], v[152:153], v[180:181]
	v_pk_fma_f32 v[212:213], v[14:15], v[152:153], v[212:213]
	v_pk_fma_f32 v[182:183], v[16:17], v[156:157], v[182:183]
	v_pk_fma_f32 v[214:215], v[14:15], v[156:157], v[214:215]
	ds_read_b128 v[126:129], v99 offset:35840
	ds_read_b128 v[130:133], v99 offset:39936
	ds_read_b128 v[134:137], v99 offset:44032
	ds_read_b128 v[138:141], v99 offset:48128
	s_waitcnt lgkmcnt(8)
; #define LAS __attribute__((address_space(3)))
; __device__ __forceinline__ float dot4(const f32x4 a, const f32x4 b) { return (a[0] * b[0] + a[1] * b[1]) + (a[2] * b[2] + a[3] * b[3]); }
; __device__ __forceinline__ void norm_rows2(const f32x4 (&xa)[4], const f32x4 (&xb)[4], const LAS float* gsa, const LAS float* sha, const LAS float* gsb, const LAS float* shb, const LAS float* WgT, ...
;     ...
;     for (int jq = 0; jq < 4; ++jq) { f32x4 sa = (f32x4){0.f, 0.f, 0.f, 0.f}, sb = sa;
; #pragma unroll
;         for (int i = 0; i < 4; ++i) { const LAS float* wp = WgT + (jq * 4) * 1024 + i * 256 + lane * 4;
;             const f32x4 w0 = *(const LAS f32x4*)wp, w1 = *(const LAS f32x4*)(wp + 1024), w2 = *(const LAS f32x4*)(wp + 2048), w3 = *(const LAS f32x4*)(wp + 3072);
;             sa += (f32x4){dot4(ya[i], w0), dot4(ya[i], w1), dot4(ya[i], w2), dot4(ya[i], w3)};
;             sb += (f32x4){dot4(yb[i], w0), dot4(yb[i], w1), dot4(yb[i], w2), dot4(yb[i], w3)}; }
;         pa[jq] = sa; pb[jq] = sb; }
	v_pk_fma_f32 v[184:185], v[20:21], v[228:229], v[184:185]
	v_pk_fma_f32 v[216:217], v[18:19], v[228:229], v[216:217]
	v_pk_fma_f32 v[186:187], v[20:21], v[232:233], v[186:187]
	v_pk_fma_f32 v[218:219], v[18:19], v[232:233], v[218:219]
	v_pk_fma_f32 v[188:189], v[20:21], v[236:237], v[188:189]
	v_pk_fma_f32 v[220:221], v[18:19], v[236:237], v[220:221]
	v_pk_fma_f32 v[190:191], v[20:21], v[240:241], v[190:191]
	v_pk_fma_f32 v[222:223], v[18:19], v[240:241], v[222:223]
	v_pk_fma_f32 v[184:185], v[16:17], v[230:231], v[184:185]
	v_pk_fma_f32 v[216:217], v[14:15], v[230:231], v[216:217]
	v_pk_fma_f32 v[186:187], v[16:17], v[234:235], v[186:187]
	v_pk_fma_f32 v[218:219], v[14:15], v[234:235], v[218:219]
	v_pk_fma_f32 v[188:189], v[16:17], v[238:239], v[188:189]
	v_pk_fma_f32 v[220:221], v[14:15], v[238:239], v[220:221]
	v_pk_fma_f32 v[190:191], v[16:17], v[242:243], v[190:191]
	v_pk_fma_f32 v[222:223], v[14:15], v[242:243], v[222:223]
	ds_read_b128 v[142:145], v99 offset:52224
	ds_read_b128 v[146:149], v99 offset:56320
	ds_read_b128 v[150:153], v99 offset:60416
	ds_read_b128 v[154:157], v99 offset:64512
	s_waitcnt lgkmcnt(8)
	v_pk_fma_f32 v[160:161], v[8:9], v[110:111], v[160:161]
	v_pk_fma_f32 v[192:193], v[12:13], v[110:111], v[192:193]
	v_pk_fma_f32 v[162:163], v[8:9], v[114:115], v[162:163]
	v_pk_fma_f32 v[194:195], v[12:13], v[114:115], v[194:195]
	v_pk_fma_f32 v[164:165], v[8:9], v[118:119], v[164:165]
	v_pk_fma_f32 v[196:197], v[12:13], v[118:119], v[196:197]
	v_pk_fma_f32 v[166:167], v[8:9], v[122:123], v[166:167]
	v_pk_fma_f32 v[198:199], v[12:13], v[122:123], v[198:199]
	v_pk_fma_f32 v[160:161], v[6:7], v[112:113], v[160:161]
	v_pk_fma_f32 v[192:193], v[10:11], v[112:113], v[192:193]
	v_pk_fma_f32 v[162:163], v[6:7], v[116:117], v[162:163]
	v_pk_fma_f32 v[194:195], v[10:11], v[116:117], v[194:195]
	v_pk_fma_f32 v[164:165], v[6:7], v[120:121], v[164:165]
	v_pk_fma_f32 v[196:197], v[10:11], v[120:121], v[196:197]
	v_pk_fma_f32 v[166:167], v[6:7], v[124:125], v[166:167]
	v_pk_fma_f32 v[198:199], v[10:11], v[124:125], v[198:199]
	ds_read_b128 v[228:231], v100 offset:52224
	ds_read_b128 v[232:235], v100 offset:56320
	ds_read_b128 v[236:239], v100 offset:60416
	ds_read_b128 v[240:243], v100 offset:64512
	s_waitcnt lgkmcnt(8)
	v_pk_fma_f32 v[168:169], v[8:9], v[126:127], v[168:169]
	v_pk_fma_f32 v[200:201], v[12:13], v[126:127], v[200:201]
	v_pk_fma_f32 v[170:171], v[8:9], v[130:131], v[170:171]
	v_pk_fma_f32 v[202:203], v[12:13], v[130:131], v[202:203]
	v_pk_fma_f32 v[172:173], v[8:9], v[134:135], v[172:173]
	v_pk_fma_f32 v[204:205], v[12:13], v[134:135], v[204:205]
	v_pk_fma_f32 v[174:175], v[8:9], v[138:139], v[174:175]
	v_pk_fma_f32 v[206:207], v[12:13], v[138:139], v[206:207]
	v_pk_fma_f32 v[168:169], v[6:7], v[128:129], v[168:169]
	v_pk_fma_f32 v[200:201], v[10:11], v[128:129], v[200:201]
	v_pk_fma_f32 v[170:171], v[6:7], v[132:133], v[170:171]
	v_pk_fma_f32 v[202:203], v[10:11], v[132:133], v[202:203]
	v_pk_fma_f32 v[172:173], v[6:7], v[136:137], v[172:173]
	v_pk_fma_f32 v[204:205], v[10:11], v[136:137], v[204:205]
	v_pk_fma_f32 v[174:175], v[6:7], v[140:141], v[174:175]
	v_pk_fma_f32 v[206:207], v[10:11], v[140:141], v[206:207]
	s_waitcnt lgkmcnt(4)
	v_pk_fma_f32 v[176:177], v[8:9], v[142:143], v[176:177]
	v_pk_fma_f32 v[208:209], v[12:13], v[142:143], v[208:209]
	v_pk_fma_f32 v[178:179], v[8:9], v[146:147], v[178:179]
	v_pk_fma_f32 v[210:211], v[12:13], v[146:147], v[210:211]
	v_pk_fma_f32 v[180:181], v[8:9], v[150:151], v[180:181]
	v_pk_fma_f32 v[212:213], v[12:13], v[150:151], v[212:213]
	v_pk_fma_f32 v[182:183], v[8:9], v[154:155], v[182:183]
	v_pk_fma_f32 v[214:215], v[12:13], v[154:155], v[214:215]
	v_pk_fma_f32 v[176:177], v[6:7], v[144:145], v[176:177]
	v_pk_fma_f32 v[208:209], v[10:11], v[144:145], v[208:209]
	v_pk_fma_f32 v[178:179], v[6:7], v[148:149], v[178:179]
	v_pk_fma_f32 v[210:211], v[10:11], v[148:149], v[210:211]
	v_pk_fma_f32 v[180:181], v[6:7], v[152:153], v[180:181]
	v_pk_fma_f32 v[212:213], v[10:11], v[152:153], v[212:213]
	v_pk_fma_f32 v[182:183], v[6:7], v[156:157], v[182:183]
	v_pk_fma_f32 v[214:215], v[10:11], v[156:157], v[214:215]
	s_waitcnt lgkmcnt(0)
	v_pk_fma_f32 v[184:185], v[8:9], v[228:229], v[184:185]
	v_pk_fma_f32 v[216:217], v[12:13], v[228:229], v[216:217]
	v_pk_fma_f32 v[186:187], v[8:9], v[232:233], v[186:187]
	v_pk_fma_f32 v[218:219], v[12:13], v[232:233], v[218:219]
	v_pk_fma_f32 v[188:189], v[8:9], v[236:237], v[188:189]
	v_pk_fma_f32 v[220:221], v[12:13], v[236:237], v[220:221]
	v_pk_fma_f32 v[190:191], v[8:9], v[240:241], v[190:191]
	v_pk_fma_f32 v[222:223], v[12:13], v[240:241], v[222:223]
	v_pk_fma_f32 v[184:185], v[6:7], v[230:231], v[184:185]
	v_pk_fma_f32 v[216:217], v[10:11], v[230:231], v[216:217]
	v_pk_fma_f32 v[186:187], v[6:7], v[234:235], v[186:187]
	v_pk_fma_f32 v[218:219], v[10:11], v[234:235], v[218:219]
	v_pk_fma_f32 v[188:189], v[6:7], v[238:239], v[188:189]
	v_pk_fma_f32 v[220:221], v[10:11], v[238:239], v[220:221]
	v_pk_fma_f32 v[190:191], v[6:7], v[242:243], v[190:191]
	v_pk_fma_f32 v[222:223], v[10:11], v[242:243], v[222:223]
	v_add_f32_e32 v22, v160, v161
	v_add_f32_e32 v23, v162, v163
	v_add_f32_e32 v24, v164, v165
	v_add_f32_e32 v25, v166, v167
	v_add_f32_e32 v78, v168, v169
	v_add_f32_e32 v79, v170, v171
	v_add_f32_e32 v80, v172, v173
	v_add_f32_e32 v81, v174, v175
	v_add_f32_e32 v86, v176, v177
	v_add_f32_e32 v87, v178, v179
	v_add_f32_e32 v88, v180, v181
	v_add_f32_e32 v89, v182, v183
	v_add_f32_e32 v2, v184, v185
	v_add_f32_e32 v3, v186, v187
	v_add_f32_e32 v0, v188, v189
	v_add_f32_e32 v1, v190, v191
	v_add_f32_e32 v26, v192, v193
	v_add_f32_e32 v27, v194, v195
; __device__ __forceinline__ float log_sigmoid(float x) { return fminf(x, 0.f) - log1pf(expf(-fabsf(x))); }
; __device__ __forceinline__ float bfly16(const f32x4 p0, const f32x4 p1, const f32x4 p2, const f32x4 p3, int lane) {
;     const bool b3 = lane & 8, b2 = lane & 4, b1 = lane & 2, b0 = lane & 1;
;     const f32x4 s0 = b3 ? p0 : p2, s1 = b3 ? p1 : p3, k0 = b3 ? p2 : p0, k1 = b3 ? p3 : p1;
;     f32x4 a, c;
;     a[0] = k0[0] + __shfl_xor(s0[0], 8); a[1] = k0[1] + __shfl_xor(s0[1], 8); a[2] = k0[2] + __shfl_xor(s0[2], 8); a[3] = k0[3] + __shfl_xor(s0[3], 8);
;     c[0] = k1[0] + __shfl_xor(s1[0], 8); c[1] = k1[1] + __shfl_xor(s1[1], 8); c[2] = k1[2] + __shfl_xor(s1[2], 8); c[3] = k1[3] + __shfl_xor(s1[3], 8);
;     const f32x4 s4 = b2 ? a : c, k4 = b2 ? c : a;
;     const float d0 = k4[0] + __shfl_xor(s4[0], 4), d1 = k4[1] + __shfl_xor(s4[1], 4), d2 = k4[2] + __shfl_xor(s4[2], 4), d3 = k4[3] + __shfl_xor(s4[3], 4);
;     const float e0 = (b1 ? d2 : d0) + __shfl_xor(b1 ? d0 : d2, 2), e1 = (b1 ? d3 : d1) + __shfl_xor(b1 ? d1 : d3, 2);
;     float q1 = (b0 ? e1 : e0) + __shfl_xor(b0 ? e0 : e1, 1);
;     q1 += __shfl_xor(q1, 16); q1 += __shfl_xor(q1, 32);
; __device__ __forceinline__ void norm_rows2(const f32x4 (&xa)[4], const f32x4 (&xb)[4], const LAS float* gsa, const LAS float* sha, const LAS float* gsb, const LAS float* shb, const LAS float* WgT, ...
;     ...
;     const float qa = bfly16(pa[0], pa[1], pa[2], pa[3], lane), qb = bfly16(pb[0], pb[1], pb[2], pb[3], lane);
;     if (lane < 16) { const float gbv = gate_b[lane]; const bool ls = (lane >> 2) & 1;
;         const float prea = qa + gbv, preb = qb + gbv;
;         ga[0] = ls ? log_sigmoid(prea) : prea; gb[0] = ls ? log_sigmoid(preb) : preb; }
	v_add_f32_e32 v28, v196, v197
	v_add_f32_e32 v29, v198, v199
	v_add_f32_e32 v82, v200, v201
	v_add_f32_e32 v83, v202, v203
	v_add_f32_e32 v84, v204, v205
	v_add_f32_e32 v85, v206, v207
	v_add_f32_e32 v90, v208, v209
	v_add_f32_e32 v91, v210, v211
	v_add_f32_e32 v92, v212, v213
	v_add_f32_e32 v93, v214, v215
	v_add_f32_e32 v12, v216, v217
	v_add_f32_e32 v13, v218, v219
	v_add_f32_e32 v10, v220, v221
	v_add_f32_e32 v11, v222, v223
	v_cndmask_b32_e64 v21, v85, v11, s[6:7]
	v_cndmask_b32_e64 v20, v84, v10, s[6:7]
	v_add_f32_dpp v110, v22, v22 row_mirror row_mask:0xf bank_mask:0x3
	v_add_f32_dpp v110, v86, v86 row_mirror row_mask:0xf bank_mask:0xc
	v_add_f32_dpp v114, v78, v78 row_mirror row_mask:0xf bank_mask:0x3
	v_add_f32_dpp v114, v2, v2 row_mirror row_mask:0xf bank_mask:0xc
	v_add_f32_dpp v118, v26, v26 row_mirror row_mask:0xf bank_mask:0x3
	v_add_f32_dpp v118, v90, v90 row_mirror row_mask:0xf bank_mask:0xc
	v_add_f32_dpp v122, v82, v82 row_mirror row_mask:0xf bank_mask:0x3
	v_add_f32_dpp v122, v12, v12 row_mirror row_mask:0xf bank_mask:0xc
	v_add_f32_dpp v111, v23, v23 row_mirror row_mask:0xf bank_mask:0x3
	v_add_f32_dpp v111, v87, v87 row_mirror row_mask:0xf bank_mask:0xc
	v_add_f32_dpp v115, v79, v79 row_mirror row_mask:0xf bank_mask:0x3
	v_add_f32_dpp v115, v3, v3 row_mirror row_mask:0xf bank_mask:0xc
	v_add_f32_dpp v119, v27, v27 row_mirror row_mask:0xf bank_mask:0x3
	v_add_f32_dpp v119, v91, v91 row_mirror row_mask:0xf bank_mask:0xc
	v_add_f32_dpp v123, v83, v83 row_mirror row_mask:0xf bank_mask:0x3
	v_add_f32_dpp v123, v13, v13 row_mirror row_mask:0xf bank_mask:0xc
	v_add_f32_dpp v112, v24, v24 row_mirror row_mask:0xf bank_mask:0x3
	v_add_f32_dpp v112, v88, v88 row_mirror row_mask:0xf bank_mask:0xc
	v_add_f32_dpp v116, v80, v80 row_mirror row_mask:0xf bank_mask:0x3
	v_add_f32_dpp v116, v0, v0 row_mirror row_mask:0xf bank_mask:0xc
	v_add_f32_dpp v120, v28, v28 row_mirror row_mask:0xf bank_mask:0x3
	v_add_f32_dpp v120, v92, v92 row_mirror row_mask:0xf bank_mask:0xc
	v_add_f32_dpp v124, v84, v84 row_mirror row_mask:0xf bank_mask:0x3
	v_add_f32_dpp v124, v10, v10 row_mirror row_mask:0xf bank_mask:0xc
	v_add_f32_dpp v113, v25, v25 row_mirror row_mask:0xf bank_mask:0x3
	v_add_f32_dpp v113, v89, v89 row_mirror row_mask:0xf bank_mask:0xc
	v_add_f32_dpp v117, v81, v81 row_mirror row_mask:0xf bank_mask:0x3
	v_add_f32_dpp v117, v1, v1 row_mirror row_mask:0xf bank_mask:0xc
	v_add_f32_dpp v121, v29, v29 row_mirror row_mask:0xf bank_mask:0x3
	v_add_f32_dpp v121, v93, v93 row_mirror row_mask:0xf bank_mask:0xc
	v_add_f32_dpp v125, v85, v85 row_mirror row_mask:0xf bank_mask:0x3
	v_add_f32_dpp v125, v11, v11 row_mirror row_mask:0xf bank_mask:0xc
	v_add_f32_dpp v126, v110, v110 row_half_mirror row_mask:0xf bank_mask:0x5
	v_add_f32_dpp v126, v114, v114 row_half_mirror row_mask:0xf bank_mask:0xa
	v_add_f32_dpp v130, v118, v118 row_half_mirror row_mask:0xf bank_mask:0x5
	v_add_f32_dpp v130, v122, v122 row_half_mirror row_mask:0xf bank_mask:0xa
	v_add_f32_dpp v127, v111, v111 row_half_mirror row_mask:0xf bank_mask:0x5
	v_add_f32_dpp v127, v115, v115 row_half_mirror row_mask:0xf bank_mask:0xa
	v_add_f32_dpp v131, v119, v119 row_half_mirror row_mask:0xf bank_mask:0x5
	v_add_f32_dpp v131, v123, v123 row_half_mirror row_mask:0xf bank_mask:0xa
	v_add_f32_dpp v128, v112, v112 row_half_mirror row_mask:0xf bank_mask:0x5
	v_add_f32_dpp v128, v116, v116 row_half_mirror row_mask:0xf bank_mask:0xa
	v_add_f32_dpp v132, v120, v120 row_half_mirror row_mask:0xf bank_mask:0x5
	v_add_f32_dpp v132, v124, v124 row_half_mirror row_mask:0xf bank_mask:0xa
	v_add_f32_dpp v129, v113, v113 row_half_mirror row_mask:0xf bank_mask:0x5
	v_add_f32_dpp v129, v117, v117 row_half_mirror row_mask:0xf bank_mask:0xa
	v_add_f32_dpp v133, v121, v121 row_half_mirror row_mask:0xf bank_mask:0x5
	v_add_f32_dpp v133, v125, v125 row_half_mirror row_mask:0xf bank_mask:0xa
	v_cndmask_b32_e64 v134, v128, v126, s[12:13]
	v_cndmask_b32_e64 v135, v126, v128, s[12:13]
	v_cndmask_b32_e64 v136, v129, v127, s[12:13]
	v_cndmask_b32_e64 v137, v127, v129, s[12:13]
	v_cndmask_b32_e64 v138, v132, v130, s[12:13]
	v_cndmask_b32_e64 v139, v130, v132, s[12:13]
	v_cndmask_b32_e64 v140, v133, v131, s[12:13]
	v_cndmask_b32_e64 v141, v131, v133, s[12:13]
	v_add_f32_dpp v134, v135, v134 quad_perm:[2,3,0,1] row_mask:0xf bank_mask:0xf
	v_add_f32_dpp v136, v137, v136 quad_perm:[2,3,0,1] row_mask:0xf bank_mask:0xf
	v_add_f32_dpp v138, v139, v138 quad_perm:[2,3,0,1] row_mask:0xf bank_mask:0xf
	v_add_f32_dpp v140, v141, v140 quad_perm:[2,3,0,1] row_mask:0xf bank_mask:0xf
	v_cndmask_b32_e64 v143, v134, v136, s[14:15]
	v_cndmask_b32_e64 v127, v138, v140, s[14:15]
	v_cndmask_b32_e64 v142, v136, v134, s[14:15]
	v_cndmask_b32_e64 v126, v140, v138, s[14:15]
	v_add_f32_dpp v1, v143, v142 quad_perm:[1,0,3,2] row_mask:0xf bank_mask:0xf
	v_add_f32_dpp v0, v127, v126 quad_perm:[1,0,3,2] row_mask:0xf bank_mask:0xf
	ds_bpermute_b32 v2, v94, v0
	ds_bpermute_b32 v3, v94, v1
	s_waitcnt lgkmcnt(0)
	v_pk_add_f32 v[0:1], v[0:1], v[2:3]
	ds_bpermute_b32 v2, v53, v0
	ds_bpermute_b32 v3, v53, v1
	s_and_saveexec_b64 s[30:31], s[16:17]
	s_cbranch_execz .LBB0_109
	global_load_dword v4, v[44:45], off
	s_waitcnt lgkmcnt(0)
	v_pk_add_f32 v[0:1], v[0:1], v[2:3]
	s_waitcnt vmcnt(0)
	v_pk_add_f32 v[0:1], v[0:1], v[4:5] op_sel_hi:[1,0]
	s_and_saveexec_b64 s[80:81], s[10:11]
	s_cbranch_execz .LBB0_108
; __device__ __forceinline__ float log_sigmoid(float x) { return fminf(x, 0.f) - log1pf(expf(-fabsf(x))); }
; __device__ __forceinline__ void norm_rows2(const f32x4 (&xa)[4], const f32x4 (&xb)[4], const LAS float* gsa, const LAS float* sha, const LAS float* gsb, const LAS float* shb, const LAS float* WgT, ...
;     ...
;     if (lane < 16) { const float gbv = gate_b[lane]; const bool ls = (lane >> 2) & 1;
;         const float prea = qa + gbv, preb = qb + gbv;
;         ga[0] = ls ? log_sigmoid(prea) : prea; gb[0] = ls ? log_sigmoid(preb) : preb; }
	v_mul_f32_e64 v2, |v0|, s35
	v_rndne_f32_e32 v3, v2
	v_sub_f32_e32 v4, v2, v3
	v_fma_f32 v2, |v0|, s35, -v2
	v_fma_f32 v2, |v0|, s47, v2
	v_add_f32_e32 v2, v4, v2
	v_exp_f32_e32 v4, v2
	v_cvt_i32_f32_e32 v3, v3
	v_cmp_ngt_f32_e64 s[28:29], |v0|, s53
	v_max_f32_e32 v2, v0, v0
	v_min_f32_e32 v2, 0, v2
	v_ldexp_f32 v3, v4, v3
	v_cndmask_b32_e64 v3, 0, v3, s[28:29]
	v_cmp_nlt_f32_e64 s[28:29], |v0|, s75
	s_nop 1
	v_cndmask_b32_e64 v30, v107, v3, s[28:29]
	v_add_f32_e32 v6, 1.0, v30
	v_add_f32_e32 v0, -1.0, v6
	v_sub_f32_e32 v3, v0, v6
	v_add_f32_e32 v3, 1.0, v3
	v_sub_f32_e32 v0, v30, v0
	v_add_f32_e32 v7, v0, v3
	v_mul_f32_e64 v0, |v1|, s35
	v_rndne_f32_e32 v3, v0
	v_sub_f32_e32 v9, v0, v3
	v_fma_f32 v0, |v1|, s35, -v0
	v_fma_f32 v0, |v1|, s47, v0
	v_add_f32_e32 v0, v9, v0
	v_exp_f32_e32 v0, v0
	v_cvt_i32_f32_e32 v9, v3
	v_cmp_ngt_f32_e64 s[28:29], |v1|, s53
	v_cvt_f64_f32_e32 v[4:5], v6
	v_frexp_exp_i32_f64_e32 v4, v[4:5]
	v_ldexp_f32 v0, v0, v9
	v_cndmask_b32_e64 v0, 0, v0, s[28:29]
	v_cmp_nlt_f32_e64 s[28:29], |v1|, s75
	v_max_f32_e32 v3, v1, v1
	v_frexp_mant_f32_e32 v8, v6
	v_cndmask_b32_e64 v31, v107, v0, s[28:29]
	v_add_f32_e32 v5, 1.0, v31
	v_add_f32_e32 v0, -1.0, v5
	v_sub_f32_e32 v1, v0, v5
	v_add_f32_e32 v1, 1.0, v1
	v_sub_f32_e32 v0, v31, v0
	v_add_f32_e32 v9, v0, v1
	v_frexp_mant_f32_e32 v10, v5
	v_cvt_f64_f32_e32 v[0:1], v5
	v_frexp_exp_i32_f64_e32 v0, v[0:1]
	v_cmp_gt_f32_e64 s[28:29], s79, v10
	v_min_f32_e32 v3, 0, v3
	s_nop 0
	v_subbrev_co_u32_e64 v22, s[28:29], 0, v0, s[28:29]
	v_cmp_gt_f32_e64 s[28:29], s79, v8
	s_nop 1
	v_subbrev_co_u32_e64 v23, s[28:29], 0, v4, s[28:29]
	v_sub_u32_e32 v1, 0, v23
	v_ldexp_f32 v0, v6, v1
	v_sub_u32_e32 v6, 0, v22
	v_ldexp_f32 v4, v7, v1
	v_ldexp_f32 v1, v5, v6
	v_ldexp_f32 v5, v9, v6
	v_pk_add_f32 v[6:7], v[0:1], 1.0 op_sel_hi:[1,0]
	v_pk_add_f32 v[14:15], v[0:1], -1.0 op_sel_hi:[1,0]
	v_pk_add_f32 v[8:9], v[6:7], -1.0 op_sel_hi:[1,0]
	v_pk_add_f32 v[16:17], v[14:15], 1.0 op_sel_hi:[1,0]
	v_pk_add_f32 v[8:9], v[0:1], v[8:9] neg_lo:[0,1] neg_hi:[0,1]
	v_pk_add_f32 v[0:1], v[0:1], v[16:17] neg_lo:[0,1] neg_hi:[0,1]
	v_pk_add_f32 v[8:9], v[4:5], v[8:9]
	v_pk_add_f32 v[0:1], v[4:5], v[0:1]
	v_pk_add_f32 v[10:11], v[6:7], v[8:9]
	v_pk_add_f32 v[4:5], v[14:15], v[0:1]
	v_rcp_f32_e32 v12, v10
	v_rcp_f32_e32 v13, v11
	v_pk_add_f32 v[6:7], v[6:7], v[10:11] neg_lo:[0,1] neg_hi:[0,1]
	v_pk_add_f32 v[14:15], v[14:15], v[4:5] neg_lo:[0,1] neg_hi:[0,1]
	v_pk_add_f32 v[6:7], v[8:9], v[6:7]
	v_pk_mul_f32 v[8:9], v[4:5], v[12:13]
	v_pk_add_f32 v[0:1], v[0:1], v[14:15]
	v_pk_mul_f32 v[14:15], v[10:11], v[8:9]
	v_cmp_neq_f32_e64 s[28:29], s77, v30
	v_pk_fma_f32 v[16:17], v[8:9], v[10:11], v[14:15] neg_lo:[0,0,1] neg_hi:[0,0,1]
	s_nop 0
	v_pk_fma_f32 v[16:17], v[8:9], v[6:7], v[16:17]
	s_nop 0
	v_pk_add_f32 v[18:19], v[14:15], v[16:17]
	s_nop 0
	v_pk_add_f32 v[20:21], v[4:5], v[18:19] neg_lo:[0,1] neg_hi:[0,1]
	v_pk_add_f32 v[14:15], v[18:19], v[14:15] neg_lo:[0,1] neg_hi:[0,1]
	v_pk_add_f32 v[4:5], v[4:5], v[20:21] neg_lo:[0,1] neg_hi:[0,1]
	s_nop 0
	v_pk_add_f32 v[4:5], v[4:5], v[18:19] neg_lo:[0,1] neg_hi:[0,1]
	s_nop 0
	v_pk_add_f32 v[0:1], v[0:1], v[4:5]
	v_pk_add_f32 v[4:5], v[14:15], v[16:17] neg_lo:[0,1] neg_hi:[0,1]
	s_nop 0
	v_pk_add_f32 v[0:1], v[4:5], v[0:1]
	s_nop 0
	v_pk_add_f32 v[4:5], v[20:21], v[0:1]
	s_nop 0
	v_pk_mul_f32 v[14:15], v[12:13], v[4:5]
	s_nop 0
	v_pk_mul_f32 v[16:17], v[10:11], v[14:15]
	s_nop 0
	v_pk_fma_f32 v[10:11], v[14:15], v[10:11], v[16:17] neg_lo:[0,0,1] neg_hi:[0,0,1]
	s_nop 0
	v_pk_fma_f32 v[6:7], v[14:15], v[6:7], v[10:11]
	v_pk_add_f32 v[10:11], v[20:21], v[4:5] neg_lo:[0,1] neg_hi:[0,1]
	s_nop 0
	v_pk_add_f32 v[0:1], v[0:1], v[10:11]
	v_pk_add_f32 v[10:11], v[16:17], v[6:7]
	s_nop 0
	v_pk_add_f32 v[18:19], v[4:5], v[10:11] neg_lo:[0,1] neg_hi:[0,1]
	v_pk_add_f32 v[16:17], v[10:11], v[16:17] neg_lo:[0,1] neg_hi:[0,1]
	v_pk_add_f32 v[4:5], v[4:5], v[18:19] neg_lo:[0,1] neg_hi:[0,1]
	s_nop 0
	v_pk_add_f32 v[4:5], v[4:5], v[10:11] neg_lo:[0,1] neg_hi:[0,1]
	s_nop 0
	v_pk_add_f32 v[0:1], v[0:1], v[4:5]
	v_pk_add_f32 v[4:5], v[16:17], v[6:7] neg_lo:[0,1] neg_hi:[0,1]
	s_nop 0
	v_pk_add_f32 v[0:1], v[4:5], v[0:1]
; __device__ __forceinline__ float log_sigmoid(float x) { return fminf(x, 0.f) - log1pf(expf(-fabsf(x))); }
; __device__ __forceinline__ void norm_rows2(const f32x4 (&xa)[4], const f32x4 (&xb)[4], const LAS float* gsa, const LAS float* sha, const LAS float* gsb, const LAS float* shb, const LAS float* WgT, ...
;     ...
;     if (lane < 16) { const float gbv = gate_b[lane]; const bool ls = (lane >> 2) & 1;
;         const float prea = qa + gbv, preb = qb + gbv;
;         ga[0] = ls ? log_sigmoid(prea) : prea; gb[0] = ls ? log_sigmoid(preb) : preb; }
	v_pk_add_f32 v[4:5], v[8:9], v[14:15]
	v_pk_add_f32 v[0:1], v[18:19], v[0:1]
	v_pk_add_f32 v[6:7], v[4:5], v[8:9] neg_lo:[0,1] neg_hi:[0,1]
	v_pk_mul_f32 v[0:1], v[12:13], v[0:1]
	v_pk_add_f32 v[6:7], v[14:15], v[6:7] neg_lo:[0,1] neg_hi:[0,1]
	v_cvt_f32_i32_e32 v9, v22
	v_pk_add_f32 v[0:1], v[6:7], v[0:1]
	v_cvt_f32_i32_e32 v8, v23
	v_pk_add_f32 v[6:7], v[4:5], v[0:1]
	v_pk_mul_f32 v[14:15], v[8:9], s[76:77] op_sel_hi:[1,0]
	v_pk_mul_f32 v[10:11], v[6:7], v[6:7]
	v_pk_add_f32 v[4:5], v[6:7], v[4:5] neg_lo:[0,1] neg_hi:[0,1]
	v_pk_fma_f32 v[12:13], v[10:11], s[52:53], v[52:53] op_sel_hi:[1,0,0]
	v_pk_add_f32 v[0:1], v[0:1], v[4:5] neg_lo:[0,1] neg_hi:[0,1]
	v_ldexp_f32 v4, v6, 1
	v_pk_fma_f32 v[12:13], v[10:11], v[12:13], s[74:75] op_sel_hi:[1,1,0]
	v_ldexp_f32 v5, v7, 1
	v_pk_mul_f32 v[6:7], v[6:7], v[10:11]
	v_pk_fma_f32 v[16:17], v[8:9], s[76:77], v[14:15] op_sel_hi:[1,0,1] neg_lo:[0,0,1] neg_hi:[0,0,1]
	v_pk_mul_f32 v[6:7], v[6:7], v[12:13]
	v_mov_b32_e32 v19, v5
	v_pk_add_f32 v[10:11], v[4:5], v[6:7]
	v_ldexp_f32 v0, v0, 1
	v_pk_add_f32 v[4:5], v[10:11], v[4:5] neg_lo:[0,1] neg_hi:[0,1]
	v_pk_fma_f32 v[8:9], v[8:9], s[78:79], v[16:17] op_sel_hi:[1,0,1]
	v_ldexp_f32 v1, v1, 1
	v_pk_add_f32 v[4:5], v[6:7], v[4:5] neg_lo:[0,1] neg_hi:[0,1]
	v_mov_b32_e32 v12, v14
	v_mov_b32_e32 v13, v7
	v_mov_b32_e32 v18, v8
	v_pk_add_f32 v[6:7], v[0:1], v[4:5]
	v_mov_b32_e32 v4, v14
	v_mov_b32_e32 v0, v8
	v_pk_add_f32 v[12:13], v[12:13], v[18:19]
	v_pk_add_f32 v[18:19], v[4:5], v[0:1]
	v_mov_b32_e32 v0, v10
	v_mov_b32_e32 v4, v6
	v_pk_add_f32 v[16:17], v[14:15], v[8:9]
	v_pk_add_f32 v[0:1], v[0:1], v[4:5]
	v_pk_add_f32 v[4:5], v[10:11], v[6:7]
	v_mov_b32_e32 v20, v16
	v_mov_b32_e32 v21, v15
	v_mov_b32_e32 v22, v4
	v_mov_b32_e32 v23, v9
	v_pk_add_f32 v[0:1], v[12:13], v[0:1]
	v_pk_add_f32 v[12:13], v[16:17], v[4:5]
	v_pk_add_f32 v[24:25], v[20:21], v[22:23]
	v_mov_b32_e32 v26, v4
	v_mov_b32_e32 v27, v13
	v_mov_b32_e32 v28, v10
	v_mov_b32_e32 v29, v17
	v_pk_add_f32 v[20:21], v[24:25], v[20:21] neg_lo:[0,1] neg_hi:[0,1]
	v_pk_add_f32 v[26:27], v[26:27], v[28:29] neg_lo:[0,1] neg_hi:[0,1]
	v_pk_add_f32 v[24:25], v[16:17], v[14:15] neg_lo:[0,1] neg_hi:[0,1]
	v_pk_add_f32 v[22:23], v[22:23], v[20:21] neg_lo:[0,1] neg_hi:[0,1]
	v_mov_b32_e32 v28, v16
	v_mov_b32_e32 v29, v13
	v_mov_b32_e32 v15, v27
	v_mov_b32_e32 v21, v11
	v_pk_add_f32 v[10:11], v[4:5], v[10:11] neg_lo:[0,1] neg_hi:[0,1]
	v_pk_add_f32 v[14:15], v[28:29], v[14:15] neg_lo:[0,1] neg_hi:[0,1]
	v_pk_add_f32 v[24:25], v[8:9], v[24:25] neg_lo:[0,1] neg_hi:[0,1]
	v_pk_add_f32 v[0:1], v[0:1], v[20:21] neg_lo:[0,1] neg_hi:[0,1]
	v_pk_add_f32 v[10:11], v[6:7], v[10:11] neg_lo:[0,1] neg_hi:[0,1]
	v_mov_b32_e32 v9, v17
	v_mov_b32_e32 v7, v5
	v_pk_add_f32 v[0:1], v[18:19], v[0:1] neg_lo:[0,1] neg_hi:[0,1]
	v_pk_add_f32 v[8:9], v[8:9], v[14:15] neg_lo:[0,1] neg_hi:[0,1]
	v_pk_add_f32 v[4:5], v[6:7], v[26:27] neg_lo:[0,1] neg_hi:[0,1]
	v_pk_add_f32 v[14:15], v[22:23], v[0:1]
	v_pk_add_f32 v[6:7], v[4:5], v[8:9]
	v_mov_b32_e32 v5, v1
	v_pk_add_f32 v[0:1], v[24:25], v[4:5]
	v_mov_b32_e32 v9, v23
	v_pk_add_f32 v[0:1], v[0:1], v[8:9] neg_lo:[0,1] neg_hi:[0,1]
	v_mov_b32_e32 v4, v6
	v_mov_b32_e32 v5, v15
	v_pk_add_f32 v[4:5], v[4:5], v[0:1] neg_lo:[0,1] neg_hi:[0,1]
	v_pk_add_f32 v[0:1], v[10:11], v[0:1] neg_lo:[0,1] neg_hi:[0,1]
	v_pk_add_f32 v[4:5], v[8:9], v[4:5] neg_lo:[0,1] neg_hi:[0,1]
	s_nop 0
	v_pk_add_f32 v[0:1], v[0:1], v[4:5]
	v_pk_add_f32 v[4:5], v[14:15], v[6:7]
	s_nop 0
	v_pk_add_f32 v[6:7], v[12:13], v[4:5]
	s_nop 0
	v_pk_add_f32 v[8:9], v[6:7], v[12:13] neg_lo:[0,1] neg_hi:[0,1]
	s_nop 0
	v_pk_add_f32 v[4:5], v[4:5], v[8:9] neg_lo:[0,1] neg_hi:[0,1]
	s_nop 0
	v_pk_add_f32 v[0:1], v[0:1], v[4:5]
	s_nop 0
	v_pk_add_f32 v[0:1], v[6:7], v[0:1]
	s_nop 0
	v_cndmask_b32_e64 v0, v107, v0, s[28:29]
	v_cmp_neq_f32_e64 s[28:29], s77, v31
	s_nop 1
	v_cndmask_b32_e64 v1, v107, v1, s[28:29]
	v_cmp_lt_f32_e64 s[28:29], |v31|, s92
	s_nop 1
	v_cndmask_b32_e64 v1, v1, v31, s[28:29]
	v_cmp_lt_f32_e64 s[28:29], |v30|, s92
	s_nop 1
	v_cndmask_b32_e64 v0, v0, v30, s[28:29]
	v_pk_add_f32 v[0:1], v[2:3], v[0:1] neg_lo:[0,1] neg_hi:[0,1]
	s_branch .LBB0_108

; #define LAS __attribute__((address_space(3)))
; __device__ __forceinline__ float bf_lo(unsigned w) { return __uint_as_float(w << 16); }
; __device__ __forceinline__ float bf_hi(unsigned w) { return __uint_as_float(w & 0xffff0000u); }
; __device__ void passA(const Params& p, LAS unsigned char* lds, int wg) {
;     ...
;         for (int rep = 0; rep < 2; ++rep) { const int it = tid + rep * 512; const int v = (it >> 8) * 16 + ((it >> 2) & 15), sg = ((it >> 6) & 3) * 32 + (it & 3) * 8;
;             const u32x4 raw = vr[rep];
;             u32x4 w; w.x = cvt_pk_bf16(bf_lo(raw.x) * e_s[sg], bf_hi(raw.x) * e_s[sg + 1]); w.y = cvt_pk_bf16(bf_lo(raw.y) * e_s[sg + 2], bf_hi(raw.y) * e_s[sg + 3]);
;             w.z = cvt_pk_bf16(bf_lo(raw.z) * e_s[sg + 4], bf_hi(raw.z) * e_s[sg + 5]); w.w = cvt_pk_bf16(bf_lo(raw.w) * e_s[sg + 6], bf_hi(raw.w) * e_s[sg + 7]);
;             *(LAS u32x4*)(Ve + v * 136 + sg) = w; }
; #pragma unroll
;         for (int rep = 0; rep < 2; ++rep) { const int it = tid + rep * 512; const int sq = (it & 15) | (((it >> 6) & 1) << 4), ko = ((it >> 4) & 3) | ((it >> 7) << 2);
;             const u32x4 r0 = kr[rep][0], r1 = kr[rep][1], r2 = kr[rep][2], r3 = kr[rep][3];
;             LAS bf16_t* dst = Kt + (ko * 8) * 136 + sq * 4;
;     ...
;             TRW(0, r0.x, r1.x, r2.x, r3.x, 0) TRW(1, r0.x, r1.x, r2.x, r3.x, 1) TRW(2, r0.y, r1.y, r2.y, r3.y, 0) TRW(3, r0.y, r1.y, r2.y, r3.y, 1)
;             TRW(4, r0.z, r1.z, r2.z, r3.z, 0) TRW(5, r0.z, r1.z, r2.z, r3.z, 1) TRW(6, r0.w, r1.w, r2.w, r3.w, 0) TRW(7, r0.w, r1.w, r2.w, r3.w, 1)
;     ...
;         }
;         __syncthreads();
;         if (st + 1 < 17) {
;             bool ic2; int ci2; const bf16_t* Kb2; const bf16_t* Vb2; passA_chunk(p, st + 1, b, h, dir, vs, ic2, ci2, Kb2, Vb2);
; #pragma unroll
;             for (int rep = 0; rep < 2; ++rep) { const int it = tid + rep * 512;
;                 vr[rep] = *(const u32x4*)(Vb2 + (size_t)it * 8);
;                 const int sq = (it & 15) | (((it >> 6) & 1) << 4), ko = ((it >> 4) & 3) | ((it >> 7) << 2); const bf16_t* src = Kb2 + (size_t)((sq >> 2) * 8 + (ko >> 2)) * 512 + ((sq & 3) * 16 + (ko & 3)) * 8;
;                 kr[rep][0] = *(const u32x4*)src; kr[rep][1] = *(const u32x4*)(src + 32); kr[rep][2] = *(const u32x4*)(src + 64); kr[rep][3] = *(const u32x4*)(src + 96); } }
.LBB0_394:
	v_add_u32_e32 v120, 0x15800, v112
	ds_read_b128 v[124:127], v120
	ds_read_b128 v[128:131], v120 offset:16
	s_add_i32 s10, s40, 0
	s_add_i32 s10, s10, 0x17908
	v_mov_b32_e32 v82, s10
	ds_read_b32 v82, v82
	s_cmp_gt_u32 s27, 15
	s_waitcnt vmcnt(13)
	v_lshlrev_b32_e32 v132, 16, v8
	v_and_b32_e32 v133, 0xffff0000, v8
	v_lshlrev_b32_e32 v134, 16, v9
	v_and_b32_e32 v135, 0xffff0000, v9
	v_lshlrev_b32_e32 v136, 16, v10
	v_and_b32_e32 v137, 0xffff0000, v10
	v_lshlrev_b32_e32 v138, 16, v11
	v_and_b32_e32 v139, 0xffff0000, v11
	s_waitcnt lgkmcnt(1)
	v_pk_mul_f32 v[132:133], v[124:125], v[132:133]
	v_pk_mul_f32 v[134:135], v[126:127], v[134:135]
	v_pk_mul_f32 v[136:137], v[128:129], v[136:137]
	v_pk_mul_f32 v[138:139], v[130:131], v[138:139]
	v_cvt_pk_bf16_f32 v114, v132, v133
	v_cvt_pk_bf16_f32 v115, v134, v135
	v_cvt_pk_bf16_f32 v116, v136, v137
	v_cvt_pk_bf16_f32 v117, v138, v139
	ds_write_b128 v106, v[114:117]
	s_waitcnt vmcnt(8)
	v_lshlrev_b32_e32 v132, 16, v20
	v_and_b32_e32 v133, 0xffff0000, v20
	v_lshlrev_b32_e32 v134, 16, v21
	v_and_b32_e32 v135, 0xffff0000, v21
	v_lshlrev_b32_e32 v136, 16, v22
	v_and_b32_e32 v137, 0xffff0000, v22
	v_lshlrev_b32_e32 v138, 16, v23
	v_and_b32_e32 v139, 0xffff0000, v23
	v_pk_mul_f32 v[132:133], v[124:125], v[132:133]
	v_pk_mul_f32 v[134:135], v[126:127], v[134:135]
	v_pk_mul_f32 v[136:137], v[128:129], v[136:137]
	v_pk_mul_f32 v[138:139], v[130:131], v[138:139]
	v_cvt_pk_bf16_f32 v114, v132, v133
	v_cvt_pk_bf16_f32 v115, v134, v135
	v_cvt_pk_bf16_f32 v116, v136, v137
	v_cvt_pk_bf16_f32 v117, v138, v139
	ds_write_b128 v107, v[114:117]
	v_perm_b32 v114, v4, v0, s54
	v_perm_b32 v115, v16, v12, s54
	v_perm_b32 v116, v4, v0, s55
	v_perm_b32 v117, v16, v12, s55
	ds_write2_b64 v108, v[114:115], v[116:117] offset1:34
	v_perm_b32 v114, v5, v1, s54
	v_perm_b32 v115, v17, v13, s54
	v_perm_b32 v116, v5, v1, s55
	v_perm_b32 v117, v17, v13, s55
	ds_write2_b64 v108, v[114:115], v[116:117] offset0:68 offset1:102
	v_perm_b32 v114, v6, v2, s54
	v_perm_b32 v115, v18, v14, s54
	v_perm_b32 v116, v6, v2, s55
	v_perm_b32 v117, v18, v14, s55
	ds_write2_b64 v108, v[114:115], v[116:117] offset0:136 offset1:170
	v_perm_b32 v114, v7, v3, s54
	v_perm_b32 v115, v19, v15, s54
	v_perm_b32 v116, v7, v3, s55
	v_perm_b32 v117, v19, v15, s55
	s_waitcnt vmcnt(6)
	ds_write2_b64 v108, v[114:115], v[116:117] offset0:204 offset1:238
	v_perm_b32 v114, v28, v24, s54
	s_waitcnt vmcnt(4)
	v_perm_b32 v115, v36, v32, s54
	v_perm_b32 v116, v28, v24, s55
	v_perm_b32 v117, v36, v32, s55
	ds_write2_b64 v109, v[114:115], v[116:117] offset1:34
	v_perm_b32 v114, v29, v25, s54
	v_perm_b32 v115, v37, v33, s54
	v_perm_b32 v116, v29, v25, s55
	v_perm_b32 v117, v37, v33, s55
	ds_write2_b64 v109, v[114:115], v[116:117] offset0:68 offset1:102
	v_perm_b32 v114, v30, v26, s54
	v_perm_b32 v115, v38, v34, s54
	v_perm_b32 v116, v30, v26, s55
	v_perm_b32 v117, v38, v34, s55
	ds_write2_b64 v109, v[114:115], v[116:117] offset0:136 offset1:170
	v_perm_b32 v114, v31, v27, s54
	v_perm_b32 v115, v39, v35, s54
	v_perm_b32 v116, v31, v27, s55
	v_perm_b32 v117, v39, v35, s55
	ds_write2_b64 v109, v[114:115], v[116:117] offset0:204 offset1:238
	s_cbranch_scc1 .Lpa_nopf
	s_add_i32 s47, s27, -1
	s_and_b64 s[10:11], s[8:9], exec
	s_cselect_b32 s10, s47, s28
	s_add_i32 s10, s10, s3
	s_lshl_b32 s11, s10, 2
	s_or_b32 s48, s11, s25
	s_ashr_i32 s49, s48, 31
	s_ashr_i32 s11, s10, 31
	s_lshl_b64 s[48:49], s[48:49], 16
	s_lshl_b64 s[10:11], s[10:11], 18
	s_add_u32 s10, s41, s10
	s_addc_u32 s11, s46, s11
	v_lshl_add_u64 v[24:25], v[102:103], 0, s[48:49]
	v_lshl_add_u64 v[0:1], s[10:11], 0, v[80:81]
	v_lshl_add_u64 v[16:17], v[24:25], 0, v[86:87]
	v_lshl_add_u64 v[20:21], s[10:11], 0, v[84:85]
	v_lshl_add_u64 v[36:37], v[24:25], 0, v[88:89]
	global_load_dwordx4 v[8:11], v[0:1], off
	s_nop 0
	global_load_dwordx4 v[0:3], v[16:17], off
	global_load_dwordx4 v[4:7], v[16:17], off offset:64
	global_load_dwordx4 v[12:15], v[16:17], off offset:128
	s_nop 0
	global_load_dwordx4 v[16:19], v[16:17], off offset:192
	s_nop 0
	global_load_dwordx4 v[20:23], v[20:21], off
	s_nop 0
	global_load_dwordx4 v[24:27], v[36:37], off
	global_load_dwordx4 v[28:31], v[36:37], off offset:64
	global_load_dwordx4 v[32:35], v[36:37], off offset:128
	s_nop 0
	global_load_dwordx4 v[36:39], v[36:37], off offset:192
	s_waitcnt lgkmcnt(0)
	s_barrier
	s_branch .LBB0_391
.Lpa_nopf:
	s_waitcnt lgkmcnt(0)
	s_barrier
	s_cbranch_scc1 .LBB0_391

; #define PG8_STAGE(bufoff, gbase, voff) do { _Pragma("unroll") for (int _i = 0; _i < 2; ++_i) \
;         __builtin_amdgcn_global_load_lds((const unsigned*)((const char*)(gbase) + (voff)[_i]), (LAS unsigned*)(lds + (bufoff) + ldsw + _i * 8192), 16, 0, 0); } while (0)
; #define PG8_WAIT_V(n) asm volatile("s_waitcnt vmcnt(" #n ")" ::: "memory")
; #define PG8_BAR __builtin_amdgcn_s_barrier()
;     __device__ __forceinline__ bool next(int i, Unit& u) const { if (i == 0) { u.pm = pm; u.pn = pn; return true; } return false; }
; template <class Epi, class Sched, bool ZERO>
; __device__ __forceinline__ void gemm_phase_acc(LAS unsigned char* lds, const Gemm g, const Sched& S, const Epi& E, f32x4 (&acc)[2][2][4][2]) {
;     ...
;     Unit cur, nxt; int ui = 0;
;     if (!S.next(0, cur)) return;
;     if constexpr (ZERO) {
; #pragma unroll
;     for (int a = 0; a < 2; ++a)
; #pragma unroll
;         for (int b = 0; b < 2; ++b)
; #pragma unroll
;             for (int m = 0; m < 4; ++m)
; #pragma unroll
;                 for (int n = 0; n < 2; ++n) acc[a][b][m][n] = (f32x4){0.f, 0.f, 0.f, 0.f};
;     }
;     bf16x8 At[4][2], B0[2][2], B1[2][2];
;     const char* cA = (const char*)g.A + (size_t)cur.pm * tstep; const char* cB = (const char*)g.Bt + (size_t)cur.pn * tstep;
;     PG8_STAGE(PG8_SB(0, 0), cB, voffB); PG8_STAGE(PG8_SA(0, 0), cA, voffA); PG8_STAGE(PG8_SB(0, 1), cB + hstep, voffB); PG8_STAGE(PG8_SA(0, 1), cA + hstep, voffA);
;     if (wr == 1) PG8_BAR;
;     PG8_WAIT_V(4); PG8_BAR;
;     PG8_STAGE(PG8_SB(1, 0), cB + kstep, voffB); PG8_STAGE(PG8_SA(1, 0), cA + kstep, voffA); PG8_STAGE(PG8_SB(1, 1), cB + hstep + kstep, voffB);
;     PG8_WAIT_V(6); PG8_BAR;
.LBB0_526:
	v_lshrrev_b32_e32 v16, 1, v11
	v_and_b32_e32 v140, 24, v16
	s_lshl_b32 s6, s6, 5
	v_and_b32_e32 v15, 15, v11
	v_lshlrev_b32_e32 v16, 1, v140
	v_lshlrev_b32_e32 v11, 2, v11
	s_and_b32 s38, s6, 0x60
	v_lshl_or_b32 v144, s7, 6, v15
	v_lshl_or_b32 v15, v15, 6, v16
	s_lshl_b32 s7, s7, 13
	v_and_b32_e32 v11, 32, v11
	s_lshl_b32 s6, s38, 7
	v_bitop3_b32 v16, v15, s7, v11 bitop3:0xde
	v_bitop3_b32 v11, v15, s6, v11 bitop3:0xde
	s_mov_b64 s[6:7], 0x80
	s_add_i32 m0, s25, 0x18000
	v_lshl_add_u64 v[6:7], v[6:7], 0, s[6:7]
	s_waitcnt vmcnt(4)
	s_barrier
	global_load_lds_dwordx4 v[6:7], off
	v_lshl_add_u64 v[4:5], v[4:5], 0, s[6:7]
	s_add_i32 m0, s25, 0x1a000
	s_add_i32 s39, s25, 0x8000
	s_add_i32 s40, s25, 0xa000
	global_load_lds_dwordx4 v[4:5], off
	v_lshl_add_u64 v[2:3], v[2:3], 0, s[6:7]
	s_mov_b32 m0, s39
	s_add_u32 s46, s0, 0x20080
	global_load_lds_dwordx4 v[2:3], off
	v_lshl_add_u64 v[0:1], v[0:1], 0, s[6:7]
	s_mov_b32 m0, s40
	s_addc_u32 s47, s1, 0
	global_load_lds_dwordx4 v[0:1], off
	s_add_i32 m0, s25, 0x1c000
	v_lshl_add_u64 v[0:1], s[46:47], 0, v[132:133]
	global_load_lds_dwordx4 v[0:1], off
	v_lshl_add_u64 v[0:1], s[46:47], 0, v[128:129]
	s_add_i32 m0, s25, 0x1e000
	s_add_u32 s10, s70, s10
	global_load_lds_dwordx4 v[0:1], off
	v_lshlrev_b32_e32 v0, 13, v13
	v_and_b32_e32 v0, 0xffffc000, v0
	v_lshl_add_u32 v0, v12, 10, v0
	v_and_b32_e32 v1, 1, v13
	v_lshl_or_b32 v0, v1, 6, v0
	s_addc_u32 s11, s71, s11
	v_lshl_add_u32 v0, v14, 1, v0
	v_mov_b32_e32 v1, v133
	v_lshl_add_u64 v[0:1], s[10:11], 0, v[0:1]
	s_mov_b64 s[46:47], 0xac20080
	v_lshl_add_u64 v[136:137], v[0:1], 0, s[46:47]
	v_lshlrev_b32_e32 v0, 13, v8
	v_and_b32_e32 v0, 0xffffc000, v0
	v_lshl_add_u32 v0, v9, 10, v0
	v_and_b32_e32 v1, 1, v8
	s_add_u32 s41, s70, s42
	v_lshl_or_b32 v0, v1, 6, v0
	s_addc_u32 s42, s71, 0
	s_waitcnt vmcnt(6)
	v_lshl_add_u32 v0, v10, 1, v0
	v_mov_b32_e32 v1, v133
	s_add_u32 s41, s41, 0x2000100
	v_lshl_add_u64 v[0:1], s[10:11], 0, v[0:1]
	s_addc_u32 s48, s42, 0
	s_add_i32 s52, s35, s44
	s_add_i32 s54, s22, s44
	s_add_i32 s56, s23, s44
	s_add_i32 s58, s33, s44
	v_lshl_add_u64 v[138:139], v[0:1], 0, s[46:47]
	s_mov_b32 s49, -2
	s_mov_b64 s[42:43], 0
	v_add_u32_e32 v141, s35, v11
	v_add_u32_e32 v142, 0, v16
	s_add_i32 s50, s25, 0xc000
	s_add_i32 s51, s25, 0xe000
	v_add_u32_e32 v143, s22, v11
	s_add_i32 s53, s52, 0x2000
	s_add_i32 s55, s54, 0x2000
	v_add_u32_e32 v145, s23, v11
	v_add_u32_e32 v146, s33, v11
	s_add_i32 s57, s56, 0x2000
	s_add_i32 s59, s58, 0x2000
	v_mov_b32_e32 v0, v133
	v_mov_b32_e32 v1, v133
	v_mov_b32_e32 v2, v133
	v_mov_b32_e32 v3, v133
	v_mov_b32_e32 v4, v133
	v_mov_b32_e32 v5, v133
	v_mov_b32_e32 v6, v133
	v_mov_b32_e32 v7, v133
	v_mov_b32_e32 v12, v133
	v_mov_b32_e32 v13, v133
	v_mov_b32_e32 v14, v133
	v_mov_b32_e32 v15, v133
	v_mov_b32_e32 v20, v133
	v_mov_b32_e32 v21, v133
	v_mov_b32_e32 v22, v133
	v_mov_b32_e32 v23, v133
	v_mov_b32_e32 v28, v133
	v_mov_b32_e32 v29, v133
	v_mov_b32_e32 v30, v133
	v_mov_b32_e32 v31, v133
	v_mov_b32_e32 v36, v133
	v_mov_b32_e32 v37, v133
	v_mov_b32_e32 v38, v133
	v_mov_b32_e32 v39, v133
	v_mov_b32_e32 v44, v133
	v_mov_b32_e32 v45, v133
	v_mov_b32_e32 v46, v133
	v_mov_b32_e32 v47, v133
	v_mov_b32_e32 v52, v133
	v_mov_b32_e32 v53, v133
	v_mov_b32_e32 v54, v133
	v_mov_b32_e32 v55, v133
	v_mov_b32_e32 v8, v133
	v_mov_b32_e32 v9, v133
	v_mov_b32_e32 v10, v133
	v_mov_b32_e32 v11, v133
	v_mov_b32_e32 v16, v133
	v_mov_b32_e32 v17, v133
	v_mov_b32_e32 v18, v133
	v_mov_b32_e32 v19, v133
	v_mov_b32_e32 v24, v133
	v_mov_b32_e32 v25, v133
	v_mov_b32_e32 v26, v133
	v_mov_b32_e32 v27, v133
	v_mov_b32_e32 v32, v133
	v_mov_b32_e32 v33, v133
	v_mov_b32_e32 v34, v133
	v_mov_b32_e32 v35, v133
	v_mov_b32_e32 v40, v133
	v_mov_b32_e32 v41, v133
	v_mov_b32_e32 v42, v133
	v_mov_b32_e32 v43, v133
	v_mov_b32_e32 v48, v133
	v_mov_b32_e32 v49, v133
	v_mov_b32_e32 v50, v133
	v_mov_b32_e32 v51, v133
	v_mov_b32_e32 v56, v133
	v_mov_b32_e32 v57, v133
	v_mov_b32_e32 v58, v133
	v_mov_b32_e32 v59, v133
	v_mov_b32_e32 v60, v133
	v_mov_b32_e32 v61, v133
	v_mov_b32_e32 v62, v133
	v_mov_b32_e32 v63, v133
	v_mov_b32_e32 v64, v133
	v_mov_b32_e32 v65, v133
	v_mov_b32_e32 v66, v133
	v_mov_b32_e32 v67, v133
	v_mov_b32_e32 v68, v133
	v_mov_b32_e32 v69, v133
	v_mov_b32_e32 v70, v133
	v_mov_b32_e32 v71, v133
	v_mov_b32_e32 v72, v133
	v_mov_b32_e32 v73, v133
	v_mov_b32_e32 v74, v133
	v_mov_b32_e32 v75, v133
	v_mov_b32_e32 v76, v133
	v_mov_b32_e32 v77, v133
	v_mov_b32_e32 v78, v133
	v_mov_b32_e32 v79, v133
	v_mov_b32_e32 v80, v133
	v_mov_b32_e32 v81, v133
	v_mov_b32_e32 v82, v133
	v_mov_b32_e32 v83, v133
	v_mov_b32_e32 v88, v133
	v_mov_b32_e32 v89, v133
	v_mov_b32_e32 v90, v133
	v_mov_b32_e32 v91, v133
	v_mov_b32_e32 v96, v133
	v_mov_b32_e32 v97, v133
	v_mov_b32_e32 v98, v133
	v_mov_b32_e32 v99, v133
	v_mov_b32_e32 v104, v133
	v_mov_b32_e32 v105, v133
	v_mov_b32_e32 v106, v133
	v_mov_b32_e32 v107, v133
	v_mov_b32_e32 v84, v133
	v_mov_b32_e32 v85, v133
	v_mov_b32_e32 v86, v133
	v_mov_b32_e32 v87, v133
	v_mov_b32_e32 v92, v133
	v_mov_b32_e32 v93, v133
	v_mov_b32_e32 v94, v133
	v_mov_b32_e32 v95, v133
	v_mov_b32_e32 v100, v133
	v_mov_b32_e32 v101, v133
	v_mov_b32_e32 v102, v133
	v_mov_b32_e32 v103, v133
	v_mov_b32_e32 v108, v133
	v_mov_b32_e32 v109, v133
	v_mov_b32_e32 v110, v133
	v_mov_b32_e32 v111, v133
	v_mov_b32_e32 v112, v133
	v_mov_b32_e32 v113, v133
	v_mov_b32_e32 v114, v133
	v_mov_b32_e32 v115, v133
	v_mov_b32_e32 v116, v133
	v_mov_b32_e32 v117, v133
	v_mov_b32_e32 v118, v133
	v_mov_b32_e32 v119, v133
	v_mov_b32_e32 v120, v133
	v_mov_b32_e32 v121, v133
	v_mov_b32_e32 v122, v133
	v_mov_b32_e32 v123, v133
	v_mov_b32_e32 v124, v133
	v_mov_b32_e32 v125, v133
	v_mov_b32_e32 v126, v133
	v_mov_b32_e32 v127, v133
	s_barrier
	s_nop 0
	s_nop 0
